# k=1 early barrier with trailing MFMA at priority 2, post-barrier wait kept
# baseline (speedup 1.0000x reference)
; #define PG8_STAGE(bufoff, gbase, voff) do { _Pragma("unroll") for (int _i = 0; _i < 2; ++_i) \
;         __builtin_amdgcn_global_load_lds((const unsigned*)((const char*)(gbase) + (voff)[_i]), (LAS unsigned*)(lds + (bufoff) + ldsw + _i * 8192), 16, 0, 0); } while (0)
; #define PG8_LDA(dst, b, h) do { _Pragma("unroll") for (int m = 0; m < 4; ++m) _Pragma("unroll") for (int k = 0; k < 2; ++k) dst[m][k] = *(const LAS bf16x8*)(lds + PG8_SA(b, h) + aoff + m * 2048 + k * 1024); } while (0)
; #define PG8_LDB(dst, b, h) do { _Pragma("unroll") for (int n = 0; n < 2; ++n) _Pragma("unroll") for (int k = 0; k < 2; ++k) dst[n][k] = *(const LAS bf16x8*)(lds + PG8_SB(b, h) + boff + n * 2048 + k * 1024); } while (0)
; #define PG8_MMA(ai, bj, At, Bt) do { __builtin_amdgcn_s_setprio(1); _Pragma("unroll") for (int m = 0; m < 4; ++m) _Pragma("unroll") for (int n = 0; n < 2; ++n) _Pragma("unroll") for (int k = 0; k < 2; ++k) \
;         acc[ai][bj][m][n] = __builtin_amdgcn_mfma_f32_16x16x32_bf16(Bt[n][k], At[m][k], acc[ai][bj][m][n], 0, 0, 0); __builtin_amdgcn_s_setprio(0); } while (0)
; #define PG8_WAIT_V(n) asm volatile("s_waitcnt vmcnt(" #n ")" ::: "memory")
; #define PG8_WAIT_L(n) asm volatile("s_waitcnt lgkmcnt(" #n ")" ::: "memory")
; #define PG8_BAR __builtin_amdgcn_s_barrier()
; #define PG8_SCHED __builtin_amdgcn_sched_barrier(0)
; template <class Epi, bool KREV = false>
; __device__ __forceinline__ void gemm_phase(LAS unsigned char* lds, const Gemm g, const StaticOrder& S, const Epi& E, int wave_s) {
;     ...
;             const bool last = (t == nt - 2);
;             const char* a1 = cA + (size_t)(t + 1) * kstep;
;             const char* a2 = last ? nA : cA + (size_t)(t + 2) * kstep; const char* b2 = last ? nB : cB + (size_t)(t + 2) * kstep;
;             const char* a3 = a2 + kstep; const char* b3 = b2 + kstep;
;             PG8_LDB(B0, 0, 0); PG8_LDB(B1, 0, 1); PG8_SCHED; PG8_LDA(At, 0, 0); PG8_STAGE(PG8_SA(1, 1), a1 + hstep, voffA);
;             PG8_WAIT_V(8); PG8_WAIT_L(0); PG8_BAR; PG8_MMA(0, 0, At, B0); PG8_MMA(0, 1, At, B1); PG8_BAR; PG8_SCHED;
;             PG8_LDA(At, 0, 1); PG8_STAGE(PG8_SB(0, 0), b2, voffB); PG8_STAGE(PG8_SB(0, 1), b2 + bh, voffB); PG8_STAGE(PG8_SA(0, 0), a2, voffA);
.LBB0_162:
	v_add_u32_e32 v138, 0x10000, v140
	ds_read_b128 v[146:149], v138
	ds_read_b128 v[150:153], v138 offset:1024
	ds_read_b128 v[154:157], v138 offset:2048
	ds_read_b128 v[158:161], v138 offset:3072
	v_add_u32_e32 v138, 0x14000, v140
	ds_read_b128 v[162:165], v138
	ds_read_b128 v[166:169], v138 offset:1024
	ds_read_b128 v[170:173], v138 offset:2048
	ds_read_b128 v[178:181], v138 offset:3072
	ds_read_b128 v[182:185], v143
	ds_read_b128 v[186:189], v143 offset:1024
	ds_read_b128 v[190:193], v143 offset:2048
	ds_read_b128 v[194:197], v143 offset:3072
	ds_read_b128 v[198:201], v143 offset:4096
	ds_read_b128 v[202:205], v143 offset:5120
	ds_read_b128 v[218:221], v143 offset:6144
	ds_read_b128 v[222:225], v143 offset:7168
	s_add_u32 s24, s22, 0xfff80080
	s_addc_u32 s25, s23, -1
	s_add_i32 s50, 0, 0x10000
	s_cmp_eq_u32 s49, 28
	s_cselect_b32 s27, s43, s25
	s_cselect_b32 s26, s44, s24
	s_cselect_b32 s25, s45, s48
	s_cselect_b32 s24, s46, s47
	s_add_i32 s52, 0, 0x14000
	s_add_i32 m0, s9, 0xc000
	s_nop 0
	global_load_lds_dwordx4 v134, s[22:23]
	s_add_i32 m0, s9, 0xe000
	s_nop 0
	global_load_lds_dwordx4 v136, s[22:23]
	s_waitcnt vmcnt(8)
	s_waitcnt lgkmcnt(0)
	s_barrier
	s_setprio 1
	s_waitcnt lgkmcnt(0)
	v_mfma_f32_16x16x32_bf16 v[124:127], v[146:149], v[182:185], v[124:127]
	v_mfma_f32_16x16x32_bf16 v[120:123], v[154:157], v[182:185], v[120:123]
	v_mfma_f32_16x16x32_bf16 v[108:111], v[146:149], v[190:193], v[108:111]
	v_mfma_f32_16x16x32_bf16 v[104:107], v[154:157], v[190:193], v[104:107]
	v_mfma_f32_16x16x32_bf16 v[92:95], v[146:149], v[198:201], v[92:95]
	v_mfma_f32_16x16x32_bf16 v[88:91], v[154:157], v[198:201], v[88:91]
	v_mfma_f32_16x16x32_bf16 v[76:79], v[146:149], v[218:221], v[76:79]
	v_mfma_f32_16x16x32_bf16 v[72:75], v[154:157], v[218:221], v[72:75]
	v_mfma_f32_16x16x32_bf16 v[124:127], v[150:153], v[186:189], v[124:127]
	v_mfma_f32_16x16x32_bf16 v[120:123], v[158:161], v[186:189], v[120:123]
	v_mfma_f32_16x16x32_bf16 v[108:111], v[150:153], v[194:197], v[108:111]
	v_mfma_f32_16x16x32_bf16 v[104:107], v[158:161], v[194:197], v[104:107]
	v_mfma_f32_16x16x32_bf16 v[92:95], v[150:153], v[202:205], v[92:95]
	v_mfma_f32_16x16x32_bf16 v[88:91], v[158:161], v[202:205], v[88:91]
	v_mfma_f32_16x16x32_bf16 v[76:79], v[150:153], v[222:225], v[76:79]
	v_mfma_f32_16x16x32_bf16 v[72:75], v[158:161], v[222:225], v[72:75]
	s_setprio 0
	s_setprio 1
	v_mfma_f32_16x16x32_bf16 v[116:119], v[162:165], v[182:185], v[116:119]
	v_mfma_f32_16x16x32_bf16 v[112:115], v[170:173], v[182:185], v[112:115]
	v_mfma_f32_16x16x32_bf16 v[100:103], v[162:165], v[190:193], v[100:103]
	v_mfma_f32_16x16x32_bf16 v[96:99], v[170:173], v[190:193], v[96:99]
	v_mfma_f32_16x16x32_bf16 v[84:87], v[162:165], v[198:201], v[84:87]
	v_mfma_f32_16x16x32_bf16 v[80:83], v[170:173], v[198:201], v[80:83]
	v_mfma_f32_16x16x32_bf16 v[68:71], v[162:165], v[218:221], v[68:71]
	v_mfma_f32_16x16x32_bf16 v[64:67], v[170:173], v[218:221], v[64:67]
	v_mfma_f32_16x16x32_bf16 v[116:119], v[166:169], v[186:189], v[116:119]
	v_mfma_f32_16x16x32_bf16 v[112:115], v[178:181], v[186:189], v[112:115]
	v_mfma_f32_16x16x32_bf16 v[100:103], v[166:169], v[194:197], v[100:103]
	v_mfma_f32_16x16x32_bf16 v[96:99], v[178:181], v[194:197], v[96:99]
	v_mfma_f32_16x16x32_bf16 v[84:87], v[166:169], v[202:205], v[84:87]
	v_mfma_f32_16x16x32_bf16 v[80:83], v[178:181], v[202:205], v[80:83]
	v_mfma_f32_16x16x32_bf16 v[68:71], v[166:169], v[222:225], v[68:71]
	s_setprio 2
	s_barrier
	v_mfma_f32_16x16x32_bf16 v[64:67], v[178:181], v[222:225], v[64:67]
	s_setprio 0
	s_add_u32 s98, s24, s2
	s_addc_u32 s99, s25, s3
	s_add_u32 s100, s26, s2
	s_addc_u32 s101, s27, s3
	s_add_i32 s50, s50, s29
	s_mov_b32 m0, s50
	ds_read_b128 v[182:185], v143 offset:16384
	ds_read_b128 v[186:189], v143 offset:17408
	ds_read_b128 v[190:193], v143 offset:18432
	ds_read_b128 v[194:197], v143 offset:19456
	ds_read_b128 v[198:201], v143 offset:20480
	ds_read_b128 v[202:205], v143 offset:21504
	ds_read_b128 v[218:221], v143 offset:22528
	ds_read_b128 v[222:225], v143 offset:23552
	global_load_lds_dwordx4 v176, s[24:25]
	s_add_i32 m0, s50, 0x2000
	s_add_u32 s50, s24, 0x80000
	s_addc_u32 s51, s25, 0
	s_add_i32 s52, s52, s29
	global_load_lds_dwordx4 v132, s[24:25]
	s_mov_b32 m0, s52
	v_lshl_add_u64 v[226:227], s[26:27], 0, v[130:131]
	global_load_lds_dwordx4 v176, s[50:51]
	s_add_i32 m0, s52, 0x2000
	s_nop 0
	global_load_lds_dwordx4 v132, s[50:51]
	s_mov_b32 m0, s9
	s_nop 0
	global_load_lds_dwordx4 v128, s[26:27]
	s_mov_b32 m0, s11
	s_nop 0
	global_load_lds_dwordx4 v130, s[26:27]
	s_waitcnt vmcnt(8)
	s_waitcnt lgkmcnt(0)
	s_barrier
; #define PG8_STAGE(bufoff, gbase, voff) do { _Pragma("unroll") for (int _i = 0; _i < 2; ++_i) \
;         __builtin_amdgcn_global_load_lds((const unsigned*)((const char*)(gbase) + (voff)[_i]), (LAS unsigned*)(lds + (bufoff) + ldsw + _i * 8192), 16, 0, 0); } while (0)
; #define PG8_LDA(dst, b, h) do { _Pragma("unroll") for (int m = 0; m < 4; ++m) _Pragma("unroll") for (int k = 0; k < 2; ++k) dst[m][k] = *(const LAS bf16x8*)(lds + PG8_SA(b, h) + aoff + m * 2048 + k * 1024); } while (0)
; #define PG8_LDB(dst, b, h) do { _Pragma("unroll") for (int n = 0; n < 2; ++n) _Pragma("unroll") for (int k = 0; k < 2; ++k) dst[n][k] = *(const LAS bf16x8*)(lds + PG8_SB(b, h) + boff + n * 2048 + k * 1024); } while (0)
; #define PG8_MMA(ai, bj, At, Bt) do { __builtin_amdgcn_s_setprio(1); _Pragma("unroll") for (int m = 0; m < 4; ++m) _Pragma("unroll") for (int n = 0; n < 2; ++n) _Pragma("unroll") for (int k = 0; k < 2; ++k) \
;         acc[ai][bj][m][n] = __builtin_amdgcn_mfma_f32_16x16x32_bf16(Bt[n][k], At[m][k], acc[ai][bj][m][n], 0, 0, 0); __builtin_amdgcn_s_setprio(0); } while (0)
; #define PG8_WAIT_V(n) asm volatile("s_waitcnt vmcnt(" #n ")" ::: "memory")
; #define PG8_WAIT_L(n) asm volatile("s_waitcnt lgkmcnt(" #n ")" ::: "memory")
; #define PG8_BAR __builtin_amdgcn_s_barrier()
; #define PG8_SCHED __builtin_amdgcn_sched_barrier(0)
; template <class Epi, bool KREV = false>
; __device__ __forceinline__ void gemm_phase(LAS unsigned char* lds, const Gemm g, const StaticOrder& S, const Epi& E, int wave_s) {
;     ...
;             PG8_WAIT_V(8); PG8_WAIT_L(0); PG8_BAR; PG8_MMA(1, 0, At, B0); PG8_MMA(1, 1, At, B1); PG8_BAR; PG8_SCHED;
;             PG8_LDB(B0, 1, 0); PG8_LDB(B1, 1, 1); PG8_SCHED; PG8_LDA(At, 1, 0); PG8_STAGE(PG8_SA(0, 1), a2 + hstep, voffA);
;             PG8_WAIT_V(8); PG8_WAIT_L(0); PG8_BAR; PG8_MMA(0, 0, At, B0); PG8_MMA(0, 1, At, B1); PG8_BAR; PG8_SCHED;
	s_setprio 1
	s_waitcnt lgkmcnt(0)
	v_mfma_f32_16x16x32_bf16 v[60:63], v[146:149], v[182:185], v[60:63]
	v_mfma_f32_16x16x32_bf16 v[56:59], v[154:157], v[182:185], v[56:59]
	v_mfma_f32_16x16x32_bf16 v[44:47], v[146:149], v[190:193], v[44:47]
	v_mfma_f32_16x16x32_bf16 v[40:43], v[154:157], v[190:193], v[40:43]
	v_mfma_f32_16x16x32_bf16 v[28:31], v[146:149], v[198:201], v[28:31]
	v_mfma_f32_16x16x32_bf16 v[24:27], v[154:157], v[198:201], v[24:27]
	v_mfma_f32_16x16x32_bf16 v[12:15], v[146:149], v[218:221], v[12:15]
	v_mfma_f32_16x16x32_bf16 v[8:11], v[154:157], v[218:221], v[8:11]
	v_mfma_f32_16x16x32_bf16 v[60:63], v[150:153], v[186:189], v[60:63]
	v_mfma_f32_16x16x32_bf16 v[56:59], v[158:161], v[186:189], v[56:59]
	v_mfma_f32_16x16x32_bf16 v[44:47], v[150:153], v[194:197], v[44:47]
	v_mfma_f32_16x16x32_bf16 v[40:43], v[158:161], v[194:197], v[40:43]
	v_mfma_f32_16x16x32_bf16 v[28:31], v[150:153], v[202:205], v[28:31]
	v_mfma_f32_16x16x32_bf16 v[24:27], v[158:161], v[202:205], v[24:27]
	v_mfma_f32_16x16x32_bf16 v[12:15], v[150:153], v[222:225], v[12:15]
	v_mfma_f32_16x16x32_bf16 v[8:11], v[158:161], v[222:225], v[8:11]
	s_setprio 0
	s_setprio 1
	v_mfma_f32_16x16x32_bf16 v[52:55], v[162:165], v[182:185], v[52:55]
	v_mfma_f32_16x16x32_bf16 v[48:51], v[170:173], v[182:185], v[48:51]
	v_mfma_f32_16x16x32_bf16 v[36:39], v[162:165], v[190:193], v[36:39]
	v_mfma_f32_16x16x32_bf16 v[32:35], v[170:173], v[190:193], v[32:35]
	v_mfma_f32_16x16x32_bf16 v[20:23], v[162:165], v[198:201], v[20:23]
	v_mfma_f32_16x16x32_bf16 v[16:19], v[170:173], v[198:201], v[16:19]
	v_mfma_f32_16x16x32_bf16 v[4:7], v[162:165], v[218:221], v[4:7]
	v_mfma_f32_16x16x32_bf16 v[0:3], v[170:173], v[218:221], v[0:3]
	v_mfma_f32_16x16x32_bf16 v[52:55], v[166:169], v[186:189], v[52:55]
	v_mfma_f32_16x16x32_bf16 v[48:51], v[178:181], v[186:189], v[48:51]
	v_mfma_f32_16x16x32_bf16 v[36:39], v[166:169], v[194:197], v[36:39]
	v_mfma_f32_16x16x32_bf16 v[32:35], v[178:181], v[194:197], v[32:35]
	v_mfma_f32_16x16x32_bf16 v[20:23], v[166:169], v[202:205], v[20:23]
	v_mfma_f32_16x16x32_bf16 v[16:19], v[178:181], v[202:205], v[16:19]
	v_mfma_f32_16x16x32_bf16 v[4:7], v[166:169], v[222:225], v[4:7]
	s_setprio 2
	s_barrier
	v_mfma_f32_16x16x32_bf16 v[0:3], v[178:181], v[222:225], v[0:3]
	s_setprio 0
	s_add_i32 s50, 0, 0x18000
	v_add_u32_e32 v145, s50, v140
	s_add_i32 s51, 0, 0x1c000
	ds_read_b128 v[146:149], v145
	ds_read_b128 v[150:153], v145 offset:1024
	ds_read_b128 v[154:157], v145 offset:2048
	ds_read_b128 v[158:161], v145 offset:3072
	v_add_u32_e32 v145, s51, v140
	ds_read_b128 v[162:165], v145
	ds_read_b128 v[166:169], v145 offset:1024
	ds_read_b128 v[170:173], v145 offset:2048
	ds_read_b128 v[178:181], v145 offset:3072
	s_add_u32 s26, s26, 0x80000
	s_addc_u32 s27, s27, 0
	s_mov_b32 m0, s36
	ds_read_b128 v[182:185], v143 offset:32768
	ds_read_b128 v[186:189], v143 offset:33792
	ds_read_b128 v[190:193], v143 offset:34816
	ds_read_b128 v[194:197], v143 offset:35840
	ds_read_b128 v[198:201], v143 offset:36864
	ds_read_b128 v[202:205], v143 offset:37888
	ds_read_b128 v[218:221], v143 offset:38912
	ds_read_b128 v[222:225], v143 offset:39936
	global_load_lds_dwordx4 v128, s[26:27]
	s_mov_b32 m0, s37
	s_nop 0
	global_load_lds_dwordx4 v130, s[26:27]
	s_waitcnt vmcnt(8)
	s_waitcnt lgkmcnt(0)
	s_barrier
	s_setprio 1
	s_waitcnt lgkmcnt(0)
	v_mfma_f32_16x16x32_bf16 v[124:127], v[146:149], v[182:185], v[124:127]
	v_mfma_f32_16x16x32_bf16 v[120:123], v[154:157], v[182:185], v[120:123]
	v_mfma_f32_16x16x32_bf16 v[108:111], v[146:149], v[190:193], v[108:111]
	v_mfma_f32_16x16x32_bf16 v[104:107], v[154:157], v[190:193], v[104:107]
	v_mfma_f32_16x16x32_bf16 v[92:95], v[146:149], v[198:201], v[92:95]
	v_mfma_f32_16x16x32_bf16 v[88:91], v[154:157], v[198:201], v[88:91]
	v_mfma_f32_16x16x32_bf16 v[76:79], v[146:149], v[218:221], v[76:79]
	v_mfma_f32_16x16x32_bf16 v[72:75], v[154:157], v[218:221], v[72:75]
	v_mfma_f32_16x16x32_bf16 v[124:127], v[150:153], v[186:189], v[124:127]
	v_mfma_f32_16x16x32_bf16 v[120:123], v[158:161], v[186:189], v[120:123]
	v_mfma_f32_16x16x32_bf16 v[108:111], v[150:153], v[194:197], v[108:111]
	v_mfma_f32_16x16x32_bf16 v[104:107], v[158:161], v[194:197], v[104:107]
	v_mfma_f32_16x16x32_bf16 v[92:95], v[150:153], v[202:205], v[92:95]
	v_mfma_f32_16x16x32_bf16 v[88:91], v[158:161], v[202:205], v[88:91]
	v_mfma_f32_16x16x32_bf16 v[76:79], v[150:153], v[222:225], v[76:79]
	v_mfma_f32_16x16x32_bf16 v[72:75], v[158:161], v[222:225], v[72:75]
	s_setprio 0
	s_setprio 1
	v_mfma_f32_16x16x32_bf16 v[116:119], v[162:165], v[182:185], v[116:119]
	v_mfma_f32_16x16x32_bf16 v[112:115], v[170:173], v[182:185], v[112:115]
	v_mfma_f32_16x16x32_bf16 v[100:103], v[162:165], v[190:193], v[100:103]
	v_mfma_f32_16x16x32_bf16 v[96:99], v[170:173], v[190:193], v[96:99]
	v_mfma_f32_16x16x32_bf16 v[84:87], v[162:165], v[198:201], v[84:87]
	v_mfma_f32_16x16x32_bf16 v[80:83], v[170:173], v[198:201], v[80:83]
	v_mfma_f32_16x16x32_bf16 v[68:71], v[162:165], v[218:221], v[68:71]
	v_mfma_f32_16x16x32_bf16 v[64:67], v[170:173], v[218:221], v[64:67]
	v_mfma_f32_16x16x32_bf16 v[116:119], v[166:169], v[186:189], v[116:119]
	v_mfma_f32_16x16x32_bf16 v[112:115], v[178:181], v[186:189], v[112:115]
	v_mfma_f32_16x16x32_bf16 v[100:103], v[166:169], v[194:197], v[100:103]
	v_mfma_f32_16x16x32_bf16 v[96:99], v[178:181], v[194:197], v[96:99]
	v_mfma_f32_16x16x32_bf16 v[84:87], v[166:169], v[202:205], v[84:87]
	v_mfma_f32_16x16x32_bf16 v[80:83], v[178:181], v[202:205], v[80:83]
	v_mfma_f32_16x16x32_bf16 v[68:71], v[166:169], v[222:225], v[68:71]
	s_setprio 2
	s_barrier
; #define PG8_STAGE(bufoff, gbase, voff) do { _Pragma("unroll") for (int _i = 0; _i < 2; ++_i) \
;         __builtin_amdgcn_global_load_lds((const unsigned*)((const char*)(gbase) + (voff)[_i]), (LAS unsigned*)(lds + (bufoff) + ldsw + _i * 8192), 16, 0, 0); } while (0)
; #define PG8_LDA(dst, b, h) do { _Pragma("unroll") for (int m = 0; m < 4; ++m) _Pragma("unroll") for (int k = 0; k < 2; ++k) dst[m][k] = *(const LAS bf16x8*)(lds + PG8_SA(b, h) + aoff + m * 2048 + k * 1024); } while (0)
; #define PG8_MMA(ai, bj, At, Bt) do { __builtin_amdgcn_s_setprio(1); _Pragma("unroll") for (int m = 0; m < 4; ++m) _Pragma("unroll") for (int n = 0; n < 2; ++n) _Pragma("unroll") for (int k = 0; k < 2; ++k) \
;         acc[ai][bj][m][n] = __builtin_amdgcn_mfma_f32_16x16x32_bf16(Bt[n][k], At[m][k], acc[ai][bj][m][n], 0, 0, 0); __builtin_amdgcn_s_setprio(0); } while (0)
; #define PG8_WAIT_V(n) asm volatile("s_waitcnt vmcnt(" #n ")" ::: "memory")
; #define PG8_WAIT_L(n) asm volatile("s_waitcnt lgkmcnt(" #n ")" ::: "memory")
; #define PG8_BAR __builtin_amdgcn_s_barrier()
; #define PG8_SCHED __builtin_amdgcn_sched_barrier(0)
; template <class Epi, bool KREV = false>
; __device__ __forceinline__ void gemm_phase(LAS unsigned char* lds, const Gemm g, const StaticOrder& S, const Epi& E, int wave_s) {
;     ...
;             PG8_LDA(At, 1, 1); PG8_STAGE(PG8_SB(1, 0), b3, voffB); PG8_STAGE(PG8_SB(1, 1), b3 + bh, voffB); PG8_STAGE(PG8_SA(1, 0), a3, voffA);
;             PG8_WAIT_V(8); PG8_WAIT_L(0); PG8_BAR; PG8_MMA(1, 0, At, B0); PG8_MMA(1, 1, At, B1); PG8_BAR; PG8_SCHED;
	v_mfma_f32_16x16x32_bf16 v[64:67], v[178:181], v[222:225], v[64:67]
	s_setprio 0
	s_add_i32 s26, s50, s29
	s_mov_b32 m0, s26
	ds_read_b128 v[182:185], v143 offset:49152
	ds_read_b128 v[186:189], v143 offset:50176
	ds_read_b128 v[190:193], v143 offset:51200
	ds_read_b128 v[194:197], v143 offset:52224
	ds_read_b128 v[198:201], v143 offset:53248
	ds_read_b128 v[202:205], v143 offset:54272
	ds_read_b128 v[218:221], v143 offset:55296
	ds_read_b128 v[222:225], v143 offset:56320
	global_load_lds_dwordx4 v176, s[98:99]
	s_add_i32 m0, s26, 0x2000
	s_add_u32 s24, s24, 0x80080
	s_addc_u32 s25, s25, 0
	s_add_i32 s26, s51, s29
	global_load_lds_dwordx4 v132, s[98:99]
	s_mov_b32 m0, s26
	s_nop 0
	global_load_lds_dwordx4 v176, s[24:25]
	s_add_i32 m0, s26, 0x2000
	s_nop 0
	global_load_lds_dwordx4 v132, s[24:25]
	s_mov_b32 m0, s38
	s_nop 0
	global_load_lds_dwordx4 v128, s[100:101]
	v_lshl_add_u64 v[138:139], v[226:227], 0, s[2:3]
	s_mov_b32 m0, s39
	s_nop 0
	global_load_lds_dwordx4 v130, s[100:101]
	s_waitcnt vmcnt(8)
	s_waitcnt lgkmcnt(0)
	s_barrier
	s_setprio 1
	s_waitcnt lgkmcnt(0)
	v_mfma_f32_16x16x32_bf16 v[60:63], v[146:149], v[182:185], v[60:63]
	v_mfma_f32_16x16x32_bf16 v[56:59], v[154:157], v[182:185], v[56:59]
	v_mfma_f32_16x16x32_bf16 v[44:47], v[146:149], v[190:193], v[44:47]
	v_mfma_f32_16x16x32_bf16 v[40:43], v[154:157], v[190:193], v[40:43]
	v_mfma_f32_16x16x32_bf16 v[28:31], v[146:149], v[198:201], v[28:31]
	v_mfma_f32_16x16x32_bf16 v[24:27], v[154:157], v[198:201], v[24:27]
	v_mfma_f32_16x16x32_bf16 v[12:15], v[146:149], v[218:221], v[12:15]
	v_mfma_f32_16x16x32_bf16 v[8:11], v[154:157], v[218:221], v[8:11]
	v_mfma_f32_16x16x32_bf16 v[60:63], v[150:153], v[186:189], v[60:63]
	v_mfma_f32_16x16x32_bf16 v[56:59], v[158:161], v[186:189], v[56:59]
	v_mfma_f32_16x16x32_bf16 v[44:47], v[150:153], v[194:197], v[44:47]
	v_mfma_f32_16x16x32_bf16 v[40:43], v[158:161], v[194:197], v[40:43]
	v_mfma_f32_16x16x32_bf16 v[28:31], v[150:153], v[202:205], v[28:31]
	v_mfma_f32_16x16x32_bf16 v[24:27], v[158:161], v[202:205], v[24:27]
	v_mfma_f32_16x16x32_bf16 v[12:15], v[150:153], v[222:225], v[12:15]
	v_mfma_f32_16x16x32_bf16 v[8:11], v[158:161], v[222:225], v[8:11]
	s_setprio 0
	s_setprio 1
	v_mfma_f32_16x16x32_bf16 v[52:55], v[162:165], v[182:185], v[52:55]
	v_mfma_f32_16x16x32_bf16 v[48:51], v[170:173], v[182:185], v[48:51]
	v_mfma_f32_16x16x32_bf16 v[36:39], v[162:165], v[190:193], v[36:39]
	v_mfma_f32_16x16x32_bf16 v[32:35], v[170:173], v[190:193], v[32:35]
	v_mfma_f32_16x16x32_bf16 v[20:23], v[162:165], v[198:201], v[20:23]
	v_mfma_f32_16x16x32_bf16 v[16:19], v[170:173], v[198:201], v[16:19]
	v_mfma_f32_16x16x32_bf16 v[4:7], v[162:165], v[218:221], v[4:7]
	v_mfma_f32_16x16x32_bf16 v[0:3], v[170:173], v[218:221], v[0:3]
	v_mfma_f32_16x16x32_bf16 v[52:55], v[166:169], v[186:189], v[52:55]
	v_mfma_f32_16x16x32_bf16 v[48:51], v[178:181], v[186:189], v[48:51]
	v_mfma_f32_16x16x32_bf16 v[36:39], v[166:169], v[194:197], v[36:39]
	v_mfma_f32_16x16x32_bf16 v[32:35], v[178:181], v[194:197], v[32:35]
	s_add_i32 s49, s49, 2
	s_add_u32 s22, s22, 0x100
	s_addc_u32 s23, s23, 0
	v_mfma_f32_16x16x32_bf16 v[20:23], v[166:169], v[202:205], v[20:23]
	s_add_u32 s47, s47, 0x100
	s_addc_u32 s48, s48, 0
	v_mfma_f32_16x16x32_bf16 v[16:19], v[178:181], v[202:205], v[16:19]
	s_cmp_gt_u32 s49, 29
	v_mfma_f32_16x16x32_bf16 v[4:7], v[166:169], v[222:225], v[4:7]
	s_setprio 2
	s_barrier
	v_mfma_f32_16x16x32_bf16 v[0:3], v[178:181], v[222:225], v[0:3]
	s_setprio 0
	s_cbranch_scc0 .LBB0_162
	s_and_b64 vcc, exec, s[18:19]
	s_cbranch_vccz .LBB0_165
	s_barrier

; #define PG8_STAGE(bufoff, gbase, voff) do { _Pragma("unroll") for (int _i = 0; _i < 2; ++_i) \
;         __builtin_amdgcn_global_load_lds((const unsigned*)((const char*)(gbase) + (voff)[_i]), (LAS unsigned*)(lds + (bufoff) + ldsw + _i * 8192), 16, 0, 0); } while (0)
; #define PG8_LDA(dst, b, h) do { _Pragma("unroll") for (int m = 0; m < 4; ++m) _Pragma("unroll") for (int k = 0; k < 2; ++k) dst[m][k] = *(const LAS bf16x8*)(lds + PG8_SA(b, h) + aoff + m * 2048 + k * 1024); } while (0)
; #define PG8_LDB(dst, b, h) do { _Pragma("unroll") for (int n = 0; n < 2; ++n) _Pragma("unroll") for (int k = 0; k < 2; ++k) dst[n][k] = *(const LAS bf16x8*)(lds + PG8_SB(b, h) + boff + n * 2048 + k * 1024); } while (0)
; #define PG8_MMA(ai, bj, At, Bt) do { __builtin_amdgcn_s_setprio(1); _Pragma("unroll") for (int m = 0; m < 4; ++m) _Pragma("unroll") for (int n = 0; n < 2; ++n) _Pragma("unroll") for (int k = 0; k < 2; ++k) \
;         acc[ai][bj][m][n] = __builtin_amdgcn_mfma_f32_16x16x32_bf16(Bt[n][k], At[m][k], acc[ai][bj][m][n], 0, 0, 0); __builtin_amdgcn_s_setprio(0); } while (0)
; #define PG8_WAIT_V(n) asm volatile("s_waitcnt vmcnt(" #n ")" ::: "memory")
; #define PG8_WAIT_L(n) asm volatile("s_waitcnt lgkmcnt(" #n ")" ::: "memory")
; #define PG8_BAR __builtin_amdgcn_s_barrier()
; #define PG8_SCHED __builtin_amdgcn_sched_barrier(0)
; template <class Epi, bool KREV = false>
; __device__ __forceinline__ void gemm_phase(LAS unsigned char* lds, const Gemm g, const StaticOrder& S, const Epi& E, int wave_s) {
;     ...
;             PG8_LDB(B0, 0, 0); PG8_LDB(B1, 0, 1); PG8_SCHED; PG8_LDA(At, 0, 0); PG8_STAGE(PG8_SA(1, 1), a1 + hstep, voffA);
;             PG8_WAIT_V(8); PG8_WAIT_L(0); PG8_BAR; PG8_MMA(0, 0, At, B0); PG8_MMA(0, 1, At, B1); PG8_BAR; PG8_SCHED;
;             PG8_LDA(At, 0, 1); PG8_STAGE(PG8_SB(0, 0), b2, voffB); PG8_STAGE(PG8_SB(0, 1), b2 + bh, voffB); PG8_STAGE(PG8_SA(0, 0), a2, voffA);
;             PG8_WAIT_V(8); PG8_WAIT_L(0); PG8_BAR; PG8_MMA(1, 0, At, B0); PG8_MMA(1, 1, At, B1); PG8_BAR; PG8_SCHED;
.LBB0_640:
	s_or_b32 s80, s9, 1
	s_lshl_b64 s[46:47], s[80:81], 7
	s_sub_u32 s27, 0, s46
	s_subb_u32 s45, 0, s47
	s_add_i32 s48, 0, 0x10000
	s_add_i32 s49, 0, 0x14000
	s_add_u32 s46, s41, s27
	s_addc_u32 s47, s42, s45
	s_add_i32 m0, s34, 0xc000
	s_nop 0
	global_load_lds_dwordx4 v156, s[46:47]
	s_add_i32 m0, s34, 0xe000
	s_nop 0
	global_load_lds_dwordx4 v154, s[46:47]
	s_waitcnt vmcnt(8)
	s_waitcnt lgkmcnt(0)
	s_barrier
	s_setprio 1
	s_waitcnt lgkmcnt(0)
	v_mfma_f32_16x16x32_bf16 v[132:135], v[112:115], v[218:221], v[132:135]
	v_mfma_f32_16x16x32_bf16 v[120:123], v[136:139], v[218:221], v[120:123]
	v_mfma_f32_16x16x32_bf16 v[108:111], v[112:115], v[226:229], v[108:111]
	v_mfma_f32_16x16x32_bf16 v[104:107], v[136:139], v[226:229], v[104:107]
	v_mfma_f32_16x16x32_bf16 v[92:95], v[112:115], v[234:237], v[92:95]
	v_mfma_f32_16x16x32_bf16 v[88:91], v[136:139], v[234:237], v[88:91]
	v_mfma_f32_16x16x32_bf16 v[76:79], v[112:115], v[242:245], v[76:79]
	v_mfma_f32_16x16x32_bf16 v[72:75], v[136:139], v[242:245], v[72:75]
	v_mfma_f32_16x16x32_bf16 v[132:135], v[124:127], v[222:225], v[132:135]
	v_mfma_f32_16x16x32_bf16 v[120:123], v[140:143], v[222:225], v[120:123]
	v_mfma_f32_16x16x32_bf16 v[108:111], v[124:127], v[230:233], v[108:111]
	v_mfma_f32_16x16x32_bf16 v[104:107], v[140:143], v[230:233], v[104:107]
	v_mfma_f32_16x16x32_bf16 v[92:95], v[124:127], v[238:241], v[92:95]
	v_mfma_f32_16x16x32_bf16 v[88:91], v[140:143], v[238:241], v[88:91]
	v_mfma_f32_16x16x32_bf16 v[76:79], v[124:127], v[246:249], v[76:79]
	v_mfma_f32_16x16x32_bf16 v[72:75], v[140:143], v[246:249], v[72:75]
	s_setprio 0
	s_setprio 1
	v_mfma_f32_16x16x32_bf16 v[128:131], v[144:147], v[218:221], v[128:131]
	v_mfma_f32_16x16x32_bf16 v[116:119], v[194:197], v[218:221], v[116:119]
	v_mfma_f32_16x16x32_bf16 v[100:103], v[144:147], v[226:229], v[100:103]
	v_mfma_f32_16x16x32_bf16 v[96:99], v[194:197], v[226:229], v[96:99]
	v_mfma_f32_16x16x32_bf16 v[84:87], v[144:147], v[234:237], v[84:87]
	v_mfma_f32_16x16x32_bf16 v[80:83], v[194:197], v[234:237], v[80:83]
	v_mfma_f32_16x16x32_bf16 v[68:71], v[144:147], v[242:245], v[68:71]
	v_mfma_f32_16x16x32_bf16 v[64:67], v[194:197], v[242:245], v[64:67]
	v_mfma_f32_16x16x32_bf16 v[128:131], v[148:151], v[222:225], v[128:131]
	v_mfma_f32_16x16x32_bf16 v[116:119], v[202:205], v[222:225], v[116:119]
	v_mfma_f32_16x16x32_bf16 v[100:103], v[148:151], v[230:233], v[100:103]
	v_mfma_f32_16x16x32_bf16 v[96:99], v[202:205], v[230:233], v[96:99]
	v_mfma_f32_16x16x32_bf16 v[84:87], v[148:151], v[238:241], v[84:87]
	v_mfma_f32_16x16x32_bf16 v[80:83], v[202:205], v[238:241], v[80:83]
	v_mfma_f32_16x16x32_bf16 v[68:71], v[148:151], v[246:249], v[68:71]
	s_setprio 2
	s_barrier
	v_mfma_f32_16x16x32_bf16 v[64:67], v[202:205], v[246:249], v[64:67]
	s_setprio 0
	s_add_u32 s98, s28, s78
	s_addc_u32 s99, s29, s79
	s_add_u32 s100, s30, s78
	s_addc_u32 s101, s31, s79
	s_add_i32 s27, s48, s1
	s_mov_b32 m0, s27
	ds_read_b128 v[218:221], v201 offset:16384
	ds_read_b128 v[222:225], v201 offset:17408
	ds_read_b128 v[226:229], v201 offset:18432
	ds_read_b128 v[230:233], v201 offset:19456
	ds_read_b128 v[234:237], v201 offset:20480
	ds_read_b128 v[238:241], v201 offset:21504
	ds_read_b128 v[242:245], v201 offset:22528
	ds_read_b128 v[246:249], v201 offset:23552
	global_load_lds_dwordx4 v176, s[28:29]
	s_add_i32 m0, s27, 0x2000
	s_add_u32 s46, s28, 0x80000
	s_addc_u32 s47, s29, 0
	s_add_i32 s27, s49, s1
	global_load_lds_dwordx4 v152, s[28:29]
	s_mov_b32 m0, s27
	s_nop 0
	global_load_lds_dwordx4 v176, s[46:47]
	s_add_i32 m0, s27, 0x2000
	s_nop 0
	global_load_lds_dwordx4 v152, s[46:47]
	s_mov_b32 m0, s34
	s_nop 0
	global_load_lds_dwordx4 v156, s[30:31]
	s_mov_b32 m0, s35
	s_nop 0
	global_load_lds_dwordx4 v154, s[30:31]
	s_waitcnt vmcnt(8)
	s_waitcnt lgkmcnt(0)
	s_barrier
	s_setprio 1
	s_waitcnt lgkmcnt(0)
	v_mfma_f32_16x16x32_bf16 v[60:63], v[112:115], v[218:221], v[60:63]
	v_mfma_f32_16x16x32_bf16 v[56:59], v[136:139], v[218:221], v[56:59]
	v_mfma_f32_16x16x32_bf16 v[44:47], v[112:115], v[226:229], v[44:47]
	v_mfma_f32_16x16x32_bf16 v[40:43], v[136:139], v[226:229], v[40:43]
	v_mfma_f32_16x16x32_bf16 v[28:31], v[112:115], v[234:237], v[28:31]
	v_mfma_f32_16x16x32_bf16 v[24:27], v[136:139], v[234:237], v[24:27]
	v_mfma_f32_16x16x32_bf16 v[12:15], v[112:115], v[242:245], v[12:15]
	v_mfma_f32_16x16x32_bf16 v[8:11], v[136:139], v[242:245], v[8:11]
	v_mfma_f32_16x16x32_bf16 v[60:63], v[124:127], v[222:225], v[60:63]
	v_mfma_f32_16x16x32_bf16 v[56:59], v[140:143], v[222:225], v[56:59]
	v_mfma_f32_16x16x32_bf16 v[44:47], v[124:127], v[230:233], v[44:47]
	v_mfma_f32_16x16x32_bf16 v[40:43], v[140:143], v[230:233], v[40:43]
	v_mfma_f32_16x16x32_bf16 v[28:31], v[124:127], v[238:241], v[28:31]
	v_mfma_f32_16x16x32_bf16 v[24:27], v[140:143], v[238:241], v[24:27]
	v_mfma_f32_16x16x32_bf16 v[12:15], v[124:127], v[246:249], v[12:15]
	v_mfma_f32_16x16x32_bf16 v[8:11], v[140:143], v[246:249], v[8:11]
	s_setprio 0
	s_setprio 1
	v_mfma_f32_16x16x32_bf16 v[52:55], v[144:147], v[218:221], v[52:55]
	v_mfma_f32_16x16x32_bf16 v[48:51], v[194:197], v[218:221], v[48:51]
	v_mfma_f32_16x16x32_bf16 v[36:39], v[144:147], v[226:229], v[36:39]
	v_mfma_f32_16x16x32_bf16 v[32:35], v[194:197], v[226:229], v[32:35]
	v_mfma_f32_16x16x32_bf16 v[20:23], v[144:147], v[234:237], v[20:23]
	v_mfma_f32_16x16x32_bf16 v[16:19], v[194:197], v[234:237], v[16:19]
	v_mfma_f32_16x16x32_bf16 v[4:7], v[144:147], v[242:245], v[4:7]
	v_mfma_f32_16x16x32_bf16 v[0:3], v[194:197], v[242:245], v[0:3]
	v_mfma_f32_16x16x32_bf16 v[52:55], v[148:151], v[222:225], v[52:55]
	v_mfma_f32_16x16x32_bf16 v[48:51], v[202:205], v[222:225], v[48:51]
	v_mfma_f32_16x16x32_bf16 v[36:39], v[148:151], v[230:233], v[36:39]
	v_mfma_f32_16x16x32_bf16 v[32:35], v[202:205], v[230:233], v[32:35]
	v_mfma_f32_16x16x32_bf16 v[20:23], v[148:151], v[238:241], v[20:23]
	v_mfma_f32_16x16x32_bf16 v[16:19], v[202:205], v[238:241], v[16:19]
	v_mfma_f32_16x16x32_bf16 v[4:7], v[148:151], v[246:249], v[4:7]
	s_setprio 2
	s_barrier
; #define PG8_STAGE(bufoff, gbase, voff) do { _Pragma("unroll") for (int _i = 0; _i < 2; ++_i) \
;         __builtin_amdgcn_global_load_lds((const unsigned*)((const char*)(gbase) + (voff)[_i]), (LAS unsigned*)(lds + (bufoff) + ldsw + _i * 8192), 16, 0, 0); } while (0)
; #define PG8_LDA(dst, b, h) do { _Pragma("unroll") for (int m = 0; m < 4; ++m) _Pragma("unroll") for (int k = 0; k < 2; ++k) dst[m][k] = *(const LAS bf16x8*)(lds + PG8_SA(b, h) + aoff + m * 2048 + k * 1024); } while (0)
; #define PG8_LDB(dst, b, h) do { _Pragma("unroll") for (int n = 0; n < 2; ++n) _Pragma("unroll") for (int k = 0; k < 2; ++k) dst[n][k] = *(const LAS bf16x8*)(lds + PG8_SB(b, h) + boff + n * 2048 + k * 1024); } while (0)
; #define PG8_MMA(ai, bj, At, Bt) do { __builtin_amdgcn_s_setprio(1); _Pragma("unroll") for (int m = 0; m < 4; ++m) _Pragma("unroll") for (int n = 0; n < 2; ++n) _Pragma("unroll") for (int k = 0; k < 2; ++k) \
;         acc[ai][bj][m][n] = __builtin_amdgcn_mfma_f32_16x16x32_bf16(Bt[n][k], At[m][k], acc[ai][bj][m][n], 0, 0, 0); __builtin_amdgcn_s_setprio(0); } while (0)
; #define PG8_WAIT_V(n) asm volatile("s_waitcnt vmcnt(" #n ")" ::: "memory")
; #define PG8_WAIT_L(n) asm volatile("s_waitcnt lgkmcnt(" #n ")" ::: "memory")
; #define PG8_BAR __builtin_amdgcn_s_barrier()
; #define PG8_SCHED __builtin_amdgcn_sched_barrier(0)
; template <class Epi, bool KREV = false>
; __device__ __forceinline__ void gemm_phase(LAS unsigned char* lds, const Gemm g, const StaticOrder& S, const Epi& E, int wave_s) {
;     ...
;             PG8_LDB(B0, 1, 0); PG8_LDB(B1, 1, 1); PG8_SCHED; PG8_LDA(At, 1, 0); PG8_STAGE(PG8_SA(0, 1), a2 + hstep, voffA);
;             PG8_WAIT_V(8); PG8_WAIT_L(0); PG8_BAR; PG8_MMA(0, 0, At, B0); PG8_MMA(0, 1, At, B1); PG8_BAR; PG8_SCHED;
;             PG8_LDA(At, 1, 1); PG8_STAGE(PG8_SB(1, 0), b3, voffB); PG8_STAGE(PG8_SB(1, 1), b3 + bh, voffB); PG8_STAGE(PG8_SA(1, 0), a3, voffA);
;             PG8_WAIT_V(8); PG8_WAIT_L(0); PG8_BAR; PG8_MMA(1, 0, At, B0); PG8_MMA(1, 1, At, B1); PG8_BAR; PG8_SCHED;
;         }
	v_mfma_f32_16x16x32_bf16 v[0:3], v[202:205], v[246:249], v[0:3]
	s_setprio 0
	s_add_i32 s27, 0, 0x18000
	s_add_i32 s45, 0, 0x1c000
	v_add_u32_e32 v140, s27, v199
	v_add_u32_e32 v202, s45, v199
	ds_read_b128 v[112:115], v140
	ds_read_b128 v[124:127], v140 offset:1024
	ds_read_b128 v[136:139], v140 offset:2048
	ds_read_b128 v[140:143], v140 offset:3072
	ds_read_b128 v[144:147], v202
	ds_read_b128 v[148:151], v202 offset:1024
	ds_read_b128 v[194:197], v202 offset:2048
	ds_read_b128 v[202:205], v202 offset:3072
	s_add_u32 s30, s30, 0x80000
	s_addc_u32 s31, s31, 0
	s_mov_b32 m0, s36
	ds_read_b128 v[218:221], v201 offset:32768
	ds_read_b128 v[222:225], v201 offset:33792
	ds_read_b128 v[226:229], v201 offset:34816
	ds_read_b128 v[230:233], v201 offset:35840
	ds_read_b128 v[234:237], v201 offset:36864
	ds_read_b128 v[238:241], v201 offset:37888
	ds_read_b128 v[242:245], v201 offset:38912
	ds_read_b128 v[246:249], v201 offset:39936
	global_load_lds_dwordx4 v156, s[30:31]
	s_mov_b32 m0, s37
	s_nop 0
	global_load_lds_dwordx4 v154, s[30:31]
	s_waitcnt vmcnt(8)
	s_waitcnt lgkmcnt(0)
	s_barrier
	s_setprio 1
	s_waitcnt lgkmcnt(0)
	v_mfma_f32_16x16x32_bf16 v[132:135], v[112:115], v[218:221], v[132:135]
	v_mfma_f32_16x16x32_bf16 v[120:123], v[136:139], v[218:221], v[120:123]
	v_mfma_f32_16x16x32_bf16 v[108:111], v[112:115], v[226:229], v[108:111]
	v_mfma_f32_16x16x32_bf16 v[104:107], v[136:139], v[226:229], v[104:107]
	v_mfma_f32_16x16x32_bf16 v[92:95], v[112:115], v[234:237], v[92:95]
	v_mfma_f32_16x16x32_bf16 v[88:91], v[136:139], v[234:237], v[88:91]
	v_mfma_f32_16x16x32_bf16 v[76:79], v[112:115], v[242:245], v[76:79]
	v_mfma_f32_16x16x32_bf16 v[72:75], v[136:139], v[242:245], v[72:75]
	v_mfma_f32_16x16x32_bf16 v[132:135], v[124:127], v[222:225], v[132:135]
	v_mfma_f32_16x16x32_bf16 v[120:123], v[140:143], v[222:225], v[120:123]
	v_mfma_f32_16x16x32_bf16 v[108:111], v[124:127], v[230:233], v[108:111]
	v_mfma_f32_16x16x32_bf16 v[104:107], v[140:143], v[230:233], v[104:107]
	v_mfma_f32_16x16x32_bf16 v[92:95], v[124:127], v[238:241], v[92:95]
	v_mfma_f32_16x16x32_bf16 v[88:91], v[140:143], v[238:241], v[88:91]
	v_mfma_f32_16x16x32_bf16 v[76:79], v[124:127], v[246:249], v[76:79]
	v_mfma_f32_16x16x32_bf16 v[72:75], v[140:143], v[246:249], v[72:75]
	s_setprio 0
	s_setprio 1
	v_mfma_f32_16x16x32_bf16 v[128:131], v[144:147], v[218:221], v[128:131]
	v_mfma_f32_16x16x32_bf16 v[116:119], v[194:197], v[218:221], v[116:119]
	v_mfma_f32_16x16x32_bf16 v[100:103], v[144:147], v[226:229], v[100:103]
	v_mfma_f32_16x16x32_bf16 v[96:99], v[194:197], v[226:229], v[96:99]
	v_mfma_f32_16x16x32_bf16 v[84:87], v[144:147], v[234:237], v[84:87]
	v_mfma_f32_16x16x32_bf16 v[80:83], v[194:197], v[234:237], v[80:83]
	v_mfma_f32_16x16x32_bf16 v[68:71], v[144:147], v[242:245], v[68:71]
	v_mfma_f32_16x16x32_bf16 v[64:67], v[194:197], v[242:245], v[64:67]
	v_mfma_f32_16x16x32_bf16 v[128:131], v[148:151], v[222:225], v[128:131]
	v_mfma_f32_16x16x32_bf16 v[116:119], v[202:205], v[222:225], v[116:119]
	v_mfma_f32_16x16x32_bf16 v[100:103], v[148:151], v[230:233], v[100:103]
	v_mfma_f32_16x16x32_bf16 v[96:99], v[202:205], v[230:233], v[96:99]
	v_mfma_f32_16x16x32_bf16 v[84:87], v[148:151], v[238:241], v[84:87]
	v_mfma_f32_16x16x32_bf16 v[80:83], v[202:205], v[238:241], v[80:83]
	v_mfma_f32_16x16x32_bf16 v[68:71], v[148:151], v[246:249], v[68:71]
	s_setprio 2
	s_barrier
	v_mfma_f32_16x16x32_bf16 v[64:67], v[202:205], v[246:249], v[64:67]
	s_setprio 0
	s_add_i32 s27, s27, s1
	s_mov_b32 m0, s27
	ds_read_b128 v[218:221], v201 offset:49152
	ds_read_b128 v[222:225], v201 offset:50176
	ds_read_b128 v[226:229], v201 offset:51200
	ds_read_b128 v[230:233], v201 offset:52224
	ds_read_b128 v[234:237], v201 offset:53248
	ds_read_b128 v[238:241], v201 offset:54272
	ds_read_b128 v[242:245], v201 offset:55296
	ds_read_b128 v[246:249], v201 offset:56320
	global_load_lds_dwordx4 v176, s[98:99]
	s_add_i32 m0, s27, 0x2000
	s_add_u32 s28, s28, 0x7ff80
	s_addc_u32 s29, s29, 0
	s_add_i32 s27, s45, s1
	global_load_lds_dwordx4 v152, s[98:99]
	s_mov_b32 m0, s27
	s_nop 0
	global_load_lds_dwordx4 v176, s[28:29]
	s_add_i32 m0, s27, 0x2000
	s_nop 0
	global_load_lds_dwordx4 v152, s[28:29]
	s_mov_b32 m0, s39
	s_nop 0
	global_load_lds_dwordx4 v156, s[100:101]
	s_mov_b32 m0, s40
	s_nop 0
	global_load_lds_dwordx4 v154, s[100:101]
	s_waitcnt vmcnt(8)
	s_waitcnt lgkmcnt(0)
	s_barrier
	s_setprio 1
	s_waitcnt lgkmcnt(0)
	v_mfma_f32_16x16x32_bf16 v[60:63], v[112:115], v[218:221], v[60:63]
	v_mfma_f32_16x16x32_bf16 v[56:59], v[136:139], v[218:221], v[56:59]
	v_mfma_f32_16x16x32_bf16 v[44:47], v[112:115], v[226:229], v[44:47]
	v_mfma_f32_16x16x32_bf16 v[40:43], v[136:139], v[226:229], v[40:43]
	v_mfma_f32_16x16x32_bf16 v[28:31], v[112:115], v[234:237], v[28:31]
	v_mfma_f32_16x16x32_bf16 v[24:27], v[136:139], v[234:237], v[24:27]
	v_mfma_f32_16x16x32_bf16 v[12:15], v[112:115], v[242:245], v[12:15]
	v_mfma_f32_16x16x32_bf16 v[8:11], v[136:139], v[242:245], v[8:11]
	v_mfma_f32_16x16x32_bf16 v[60:63], v[124:127], v[222:225], v[60:63]
	v_mfma_f32_16x16x32_bf16 v[56:59], v[140:143], v[222:225], v[56:59]
	v_mfma_f32_16x16x32_bf16 v[44:47], v[124:127], v[230:233], v[44:47]
	v_mfma_f32_16x16x32_bf16 v[40:43], v[140:143], v[230:233], v[40:43]
	v_mfma_f32_16x16x32_bf16 v[28:31], v[124:127], v[238:241], v[28:31]
	v_mfma_f32_16x16x32_bf16 v[24:27], v[140:143], v[238:241], v[24:27]
	v_mfma_f32_16x16x32_bf16 v[12:15], v[124:127], v[246:249], v[12:15]
	v_mfma_f32_16x16x32_bf16 v[8:11], v[140:143], v[246:249], v[8:11]
	s_setprio 0
	s_setprio 1
	v_mfma_f32_16x16x32_bf16 v[52:55], v[144:147], v[218:221], v[52:55]
	v_mfma_f32_16x16x32_bf16 v[48:51], v[194:197], v[218:221], v[48:51]
	v_mfma_f32_16x16x32_bf16 v[36:39], v[144:147], v[226:229], v[36:39]
	v_mfma_f32_16x16x32_bf16 v[32:35], v[194:197], v[226:229], v[32:35]
	v_mfma_f32_16x16x32_bf16 v[20:23], v[144:147], v[234:237], v[20:23]
	v_mfma_f32_16x16x32_bf16 v[16:19], v[194:197], v[234:237], v[16:19]
	v_mfma_f32_16x16x32_bf16 v[4:7], v[144:147], v[242:245], v[4:7]
	v_mfma_f32_16x16x32_bf16 v[0:3], v[194:197], v[242:245], v[0:3]
	v_mfma_f32_16x16x32_bf16 v[52:55], v[148:151], v[222:225], v[52:55]
	v_mfma_f32_16x16x32_bf16 v[48:51], v[202:205], v[222:225], v[48:51]
	v_mfma_f32_16x16x32_bf16 v[36:39], v[148:151], v[230:233], v[36:39]
	v_mfma_f32_16x16x32_bf16 v[32:35], v[202:205], v[230:233], v[32:35]
	s_cmp_gt_u32 s9, 29
	s_mov_b32 s9, s26
	v_mfma_f32_16x16x32_bf16 v[20:23], v[148:151], v[238:241], v[20:23]
	v_mfma_f32_16x16x32_bf16 v[16:19], v[202:205], v[238:241], v[16:19]
	v_mfma_f32_16x16x32_bf16 v[4:7], v[148:151], v[246:249], v[4:7]
	s_setprio 2
	s_barrier
	v_mfma_f32_16x16x32_bf16 v[0:3], v[202:205], v[246:249], v[0:3]
	s_setprio 0
	s_cbranch_scc1 .LBB0_645

; #define PG8_STAGE(bufoff, gbase, voff) do { _Pragma("unroll") for (int _i = 0; _i < 2; ++_i) \
;         __builtin_amdgcn_global_load_lds((const unsigned*)((const char*)(gbase) + (voff)[_i]), (LAS unsigned*)(lds + (bufoff) + ldsw + _i * 8192), 16, 0, 0); } while (0)
; #define PG8_LDA(dst, b, h) do { _Pragma("unroll") for (int m = 0; m < 4; ++m) _Pragma("unroll") for (int k = 0; k < 2; ++k) dst[m][k] = *(const LAS bf16x8*)(lds + PG8_SA(b, h) + aoff + m * 2048 + k * 1024); } while (0)
; #define PG8_LDB(dst, b, h) do { _Pragma("unroll") for (int n = 0; n < 2; ++n) _Pragma("unroll") for (int k = 0; k < 2; ++k) dst[n][k] = *(const LAS bf16x8*)(lds + PG8_SB(b, h) + boff + n * 2048 + k * 1024); } while (0)
; #define PG8_MMA(ai, bj, At, Bt) do { __builtin_amdgcn_s_setprio(1); _Pragma("unroll") for (int m = 0; m < 4; ++m) _Pragma("unroll") for (int n = 0; n < 2; ++n) _Pragma("unroll") for (int k = 0; k < 2; ++k) \
;         acc[ai][bj][m][n] = __builtin_amdgcn_mfma_f32_16x16x32_bf16(Bt[n][k], At[m][k], acc[ai][bj][m][n], 0, 0, 0); __builtin_amdgcn_s_setprio(0); } while (0)
; #define PG8_WAIT_V(n) asm volatile("s_waitcnt vmcnt(" #n ")" ::: "memory")
; #define PG8_WAIT_L(n) asm volatile("s_waitcnt lgkmcnt(" #n ")" ::: "memory")
; #define PG8_BAR __builtin_amdgcn_s_barrier()
; #define PG8_SCHED __builtin_amdgcn_sched_barrier(0)
; template <class Epi, bool KREV = false>
; __device__ __forceinline__ void gemm_phase(LAS unsigned char* lds, const Gemm g, const StaticOrder& S, const Epi& E, int wave_s) {
;     ...
;             const char* a2 = last ? nA : cA + (size_t)(t + 2) * kstep; const char* b2 = last ? nB : cB + (size_t)(t + 2) * kstep;
;             const char* a3 = a2 + kstep; const char* b3 = b2 + kstep;
;             PG8_LDB(B0, 0, 0); PG8_LDB(B1, 0, 1); PG8_SCHED; PG8_LDA(At, 0, 0); PG8_STAGE(PG8_SA(1, 1), a1 + hstep, voffA);
;             PG8_WAIT_V(8); PG8_WAIT_L(0); PG8_BAR; PG8_MMA(0, 0, At, B0); PG8_MMA(0, 1, At, B1); PG8_BAR; PG8_SCHED;
;             PG8_LDA(At, 0, 1); PG8_STAGE(PG8_SB(0, 0), b2, voffB); PG8_STAGE(PG8_SB(0, 1), b2 + bh, voffB); PG8_STAGE(PG8_SA(0, 0), a2, voffA);
;             PG8_WAIT_V(8); PG8_WAIT_L(0); PG8_BAR; PG8_MMA(1, 0, At, B0); PG8_MMA(1, 1, At, B1); PG8_BAR; PG8_SCHED;
.LBB0_836:
	v_add_u32_e32 v154, 0x10000, v135
	v_add_u32_e32 v170, 0x14000, v135
	ds_read_b128 v[142:145], v154
	ds_read_b128 v[146:149], v154 offset:1024
	ds_read_b128 v[150:153], v154 offset:2048
	ds_read_b128 v[154:157], v154 offset:3072
	ds_read_b128 v[158:161], v170
	ds_read_b128 v[162:165], v170 offset:1024
	ds_read_b128 v[166:169], v170 offset:2048
	ds_read_b128 v[170:173], v170 offset:3072
	ds_read_b128 v[178:181], v194
	ds_read_b128 v[182:185], v194 offset:1024
	ds_read_b128 v[186:189], v194 offset:2048
	ds_read_b128 v[196:199], v194 offset:3072
	ds_read_b128 v[200:203], v194 offset:4096
	ds_read_b128 v[204:207], v194 offset:5120
	ds_read_b128 v[218:221], v194 offset:6144
	ds_read_b128 v[222:225], v194 offset:7168
	s_add_u32 s56, s54, 0xfff80080
	s_addc_u32 s57, s55, -1
	s_add_i32 s84, 0, 0x10000
	s_cmp_eq_u32 s83, 28
	s_cselect_b32 s59, s73, s57
	s_cselect_b32 s58, s74, s56
	s_cselect_b32 s57, s75, s82
	s_cselect_b32 s56, s77, s80
	s_add_i32 s86, 0, 0x14000
	s_add_i32 m0, s19, 0xc000
	s_nop 0
	global_load_lds_dwordx4 v138, s[54:55]
	s_add_i32 m0, s19, 0xe000
	s_nop 0
	global_load_lds_dwordx4 v140, s[54:55]
	s_waitcnt vmcnt(8)
	s_waitcnt lgkmcnt(0)
	s_barrier
	s_setprio 1
	s_waitcnt lgkmcnt(0)
	v_mfma_f32_16x16x32_bf16 v[124:127], v[142:145], v[178:181], v[124:127]
	v_mfma_f32_16x16x32_bf16 v[120:123], v[150:153], v[178:181], v[120:123]
	v_mfma_f32_16x16x32_bf16 v[68:71], v[142:145], v[186:189], v[68:71]
	v_mfma_f32_16x16x32_bf16 v[64:67], v[150:153], v[186:189], v[64:67]
	v_mfma_f32_16x16x32_bf16 v[60:63], v[142:145], v[200:203], v[60:63]
	v_mfma_f32_16x16x32_bf16 v[20:23], v[150:153], v[200:203], v[20:23]
	v_mfma_f32_16x16x32_bf16 v[108:111], v[142:145], v[218:221], v[108:111]
	v_mfma_f32_16x16x32_bf16 v[104:107], v[150:153], v[218:221], v[104:107]
	v_mfma_f32_16x16x32_bf16 v[124:127], v[146:149], v[182:185], v[124:127]
	v_mfma_f32_16x16x32_bf16 v[120:123], v[154:157], v[182:185], v[120:123]
	v_mfma_f32_16x16x32_bf16 v[68:71], v[146:149], v[196:199], v[68:71]
	v_mfma_f32_16x16x32_bf16 v[64:67], v[154:157], v[196:199], v[64:67]
	v_mfma_f32_16x16x32_bf16 v[60:63], v[146:149], v[204:207], v[60:63]
	v_mfma_f32_16x16x32_bf16 v[20:23], v[154:157], v[204:207], v[20:23]
	v_mfma_f32_16x16x32_bf16 v[108:111], v[146:149], v[222:225], v[108:111]
	v_mfma_f32_16x16x32_bf16 v[104:107], v[154:157], v[222:225], v[104:107]
	s_setprio 0
	s_setprio 1
	v_mfma_f32_16x16x32_bf16 v[116:119], v[158:161], v[178:181], v[116:119]
	v_mfma_f32_16x16x32_bf16 v[112:115], v[166:169], v[178:181], v[112:115]
	v_mfma_f32_16x16x32_bf16 v[52:55], v[158:161], v[186:189], v[52:55]
	v_mfma_f32_16x16x32_bf16 v[48:51], v[166:169], v[186:189], v[48:51]
	v_mfma_f32_16x16x32_bf16 v[44:47], v[158:161], v[200:203], v[44:47]
	v_mfma_f32_16x16x32_bf16 v[16:19], v[166:169], v[200:203], v[16:19]
	v_mfma_f32_16x16x32_bf16 v[100:103], v[158:161], v[218:221], v[100:103]
	v_mfma_f32_16x16x32_bf16 v[96:99], v[166:169], v[218:221], v[96:99]
	v_mfma_f32_16x16x32_bf16 v[116:119], v[162:165], v[182:185], v[116:119]
	v_mfma_f32_16x16x32_bf16 v[112:115], v[170:173], v[182:185], v[112:115]
	v_mfma_f32_16x16x32_bf16 v[52:55], v[162:165], v[196:199], v[52:55]
	v_mfma_f32_16x16x32_bf16 v[48:51], v[170:173], v[196:199], v[48:51]
	v_mfma_f32_16x16x32_bf16 v[44:47], v[162:165], v[204:207], v[44:47]
	v_mfma_f32_16x16x32_bf16 v[16:19], v[170:173], v[204:207], v[16:19]
	v_mfma_f32_16x16x32_bf16 v[100:103], v[162:165], v[222:225], v[100:103]
	s_setprio 2
	s_barrier
	v_mfma_f32_16x16x32_bf16 v[96:99], v[170:173], v[222:225], v[96:99]
	s_setprio 0
	s_add_u32 s98, s56, s2
	s_addc_u32 s99, s57, s3
	s_add_u32 s100, s58, s2
	s_addc_u32 s101, s59, s3
	s_add_i32 s84, s84, s66
	s_mov_b32 m0, s84
	ds_read_b128 v[178:181], v194 offset:16384
	ds_read_b128 v[182:185], v194 offset:17408
	ds_read_b128 v[186:189], v194 offset:18432
	ds_read_b128 v[196:199], v194 offset:19456
	ds_read_b128 v[200:203], v194 offset:20480
	ds_read_b128 v[204:207], v194 offset:21504
	ds_read_b128 v[218:221], v194 offset:22528
	ds_read_b128 v[222:225], v194 offset:23552
	global_load_lds_dwordx4 v176, s[56:57]
	s_add_i32 m0, s84, 0x2000
	s_add_u32 s84, s56, 0x1600000
	s_addc_u32 s85, s57, 0
	s_add_i32 s86, s86, s66
	global_load_lds_dwordx4 v132, s[56:57]
	s_mov_b32 m0, s86
	s_nop 0
	global_load_lds_dwordx4 v176, s[84:85]
	s_add_i32 m0, s86, 0x2000
	s_nop 0
	global_load_lds_dwordx4 v132, s[84:85]
	s_mov_b32 m0, s19
	s_nop 0
	global_load_lds_dwordx4 v128, s[58:59]
	s_mov_b32 m0, s21
	s_nop 0
	global_load_lds_dwordx4 v130, s[58:59]
	s_waitcnt vmcnt(8)
	s_waitcnt lgkmcnt(0)
	s_barrier
; #define PG8_STAGE(bufoff, gbase, voff) do { _Pragma("unroll") for (int _i = 0; _i < 2; ++_i) \
;         __builtin_amdgcn_global_load_lds((const unsigned*)((const char*)(gbase) + (voff)[_i]), (LAS unsigned*)(lds + (bufoff) + ldsw + _i * 8192), 16, 0, 0); } while (0)
; #define PG8_LDA(dst, b, h) do { _Pragma("unroll") for (int m = 0; m < 4; ++m) _Pragma("unroll") for (int k = 0; k < 2; ++k) dst[m][k] = *(const LAS bf16x8*)(lds + PG8_SA(b, h) + aoff + m * 2048 + k * 1024); } while (0)
; #define PG8_LDB(dst, b, h) do { _Pragma("unroll") for (int n = 0; n < 2; ++n) _Pragma("unroll") for (int k = 0; k < 2; ++k) dst[n][k] = *(const LAS bf16x8*)(lds + PG8_SB(b, h) + boff + n * 2048 + k * 1024); } while (0)
; #define PG8_MMA(ai, bj, At, Bt) do { __builtin_amdgcn_s_setprio(1); _Pragma("unroll") for (int m = 0; m < 4; ++m) _Pragma("unroll") for (int n = 0; n < 2; ++n) _Pragma("unroll") for (int k = 0; k < 2; ++k) \
;         acc[ai][bj][m][n] = __builtin_amdgcn_mfma_f32_16x16x32_bf16(Bt[n][k], At[m][k], acc[ai][bj][m][n], 0, 0, 0); __builtin_amdgcn_s_setprio(0); } while (0)
; #define PG8_WAIT_V(n) asm volatile("s_waitcnt vmcnt(" #n ")" ::: "memory")
; #define PG8_WAIT_L(n) asm volatile("s_waitcnt lgkmcnt(" #n ")" ::: "memory")
; #define PG8_BAR __builtin_amdgcn_s_barrier()
; #define PG8_SCHED __builtin_amdgcn_sched_barrier(0)
; template <class Epi, bool KREV = false>
; __device__ __forceinline__ void gemm_phase(LAS unsigned char* lds, const Gemm g, const StaticOrder& S, const Epi& E, int wave_s) {
;     ...
;             PG8_WAIT_V(8); PG8_WAIT_L(0); PG8_BAR; PG8_MMA(1, 0, At, B0); PG8_MMA(1, 1, At, B1); PG8_BAR; PG8_SCHED;
;             PG8_LDB(B0, 1, 0); PG8_LDB(B1, 1, 1); PG8_SCHED; PG8_LDA(At, 1, 0); PG8_STAGE(PG8_SA(0, 1), a2 + hstep, voffA);
;             PG8_WAIT_V(8); PG8_WAIT_L(0); PG8_BAR; PG8_MMA(0, 0, At, B0); PG8_MMA(0, 1, At, B1); PG8_BAR; PG8_SCHED;
	s_setprio 1
	s_waitcnt lgkmcnt(0)
	v_mfma_f32_16x16x32_bf16 v[92:95], v[142:145], v[178:181], v[92:95]
	v_mfma_f32_16x16x32_bf16 v[88:91], v[150:153], v[178:181], v[88:91]
	v_mfma_f32_16x16x32_bf16 v[36:39], v[142:145], v[186:189], v[36:39]
	v_mfma_f32_16x16x32_bf16 v[12:15], v[150:153], v[186:189], v[12:15]
	v_mfma_f32_16x16x32_bf16 v[32:35], v[142:145], v[200:203], v[32:35]
	v_mfma_f32_16x16x32_bf16 v[4:7], v[150:153], v[200:203], v[4:7]
	v_mfma_f32_16x16x32_bf16 v[76:79], v[142:145], v[218:221], v[76:79]
	v_mfma_f32_16x16x32_bf16 v[56:59], v[150:153], v[218:221], v[56:59]
	v_mfma_f32_16x16x32_bf16 v[92:95], v[146:149], v[182:185], v[92:95]
	v_mfma_f32_16x16x32_bf16 v[88:91], v[154:157], v[182:185], v[88:91]
	v_mfma_f32_16x16x32_bf16 v[36:39], v[146:149], v[196:199], v[36:39]
	v_mfma_f32_16x16x32_bf16 v[12:15], v[154:157], v[196:199], v[12:15]
	v_mfma_f32_16x16x32_bf16 v[32:35], v[146:149], v[204:207], v[32:35]
	v_mfma_f32_16x16x32_bf16 v[4:7], v[154:157], v[204:207], v[4:7]
	v_mfma_f32_16x16x32_bf16 v[76:79], v[146:149], v[222:225], v[76:79]
	v_mfma_f32_16x16x32_bf16 v[56:59], v[154:157], v[222:225], v[56:59]
	s_setprio 0
	s_setprio 1
	v_mfma_f32_16x16x32_bf16 v[84:87], v[158:161], v[178:181], v[84:87]
	v_mfma_f32_16x16x32_bf16 v[80:83], v[166:169], v[178:181], v[80:83]
	v_mfma_f32_16x16x32_bf16 v[28:31], v[158:161], v[186:189], v[28:31]
	v_mfma_f32_16x16x32_bf16 v[8:11], v[166:169], v[186:189], v[8:11]
	v_mfma_f32_16x16x32_bf16 v[24:27], v[158:161], v[200:203], v[24:27]
	v_mfma_f32_16x16x32_bf16 v[0:3], v[166:169], v[200:203], v[0:3]
	v_mfma_f32_16x16x32_bf16 v[72:75], v[158:161], v[218:221], v[72:75]
	v_mfma_f32_16x16x32_bf16 v[40:43], v[166:169], v[218:221], v[40:43]
	v_mfma_f32_16x16x32_bf16 v[84:87], v[162:165], v[182:185], v[84:87]
	v_mfma_f32_16x16x32_bf16 v[80:83], v[170:173], v[182:185], v[80:83]
	v_mfma_f32_16x16x32_bf16 v[28:31], v[162:165], v[196:199], v[28:31]
	v_mfma_f32_16x16x32_bf16 v[8:11], v[170:173], v[196:199], v[8:11]
	v_mfma_f32_16x16x32_bf16 v[24:27], v[162:165], v[204:207], v[24:27]
	v_mfma_f32_16x16x32_bf16 v[0:3], v[170:173], v[204:207], v[0:3]
	v_mfma_f32_16x16x32_bf16 v[72:75], v[162:165], v[222:225], v[72:75]
	s_setprio 2
	s_barrier
	v_mfma_f32_16x16x32_bf16 v[40:43], v[170:173], v[222:225], v[40:43]
	s_setprio 0
	s_add_i32 s84, 0, 0x18000
	s_add_i32 s85, 0, 0x1c000
	v_add_u32_e32 v154, s84, v135
	v_add_u32_e32 v170, s85, v135
	ds_read_b128 v[142:145], v154
	ds_read_b128 v[146:149], v154 offset:1024
	ds_read_b128 v[150:153], v154 offset:2048
	ds_read_b128 v[154:157], v154 offset:3072
	ds_read_b128 v[158:161], v170
	ds_read_b128 v[162:165], v170 offset:1024
	ds_read_b128 v[166:169], v170 offset:2048
	ds_read_b128 v[170:173], v170 offset:3072
	s_add_u32 s58, s58, 0x80000
	s_addc_u32 s59, s59, 0
	s_mov_b32 m0, s67
	ds_read_b128 v[178:181], v194 offset:32768
	ds_read_b128 v[182:185], v194 offset:33792
	ds_read_b128 v[186:189], v194 offset:34816
	ds_read_b128 v[196:199], v194 offset:35840
	ds_read_b128 v[200:203], v194 offset:36864
	ds_read_b128 v[204:207], v194 offset:37888
	ds_read_b128 v[218:221], v194 offset:38912
	ds_read_b128 v[222:225], v194 offset:39936
	global_load_lds_dwordx4 v128, s[58:59]
	s_mov_b32 m0, s68
	s_nop 0
	global_load_lds_dwordx4 v130, s[58:59]
	s_waitcnt vmcnt(8)
	s_waitcnt lgkmcnt(0)
	s_barrier
	s_setprio 1
	s_waitcnt lgkmcnt(0)
	v_mfma_f32_16x16x32_bf16 v[124:127], v[142:145], v[178:181], v[124:127]
	v_mfma_f32_16x16x32_bf16 v[120:123], v[150:153], v[178:181], v[120:123]
	v_mfma_f32_16x16x32_bf16 v[68:71], v[142:145], v[186:189], v[68:71]
	v_mfma_f32_16x16x32_bf16 v[64:67], v[150:153], v[186:189], v[64:67]
	v_mfma_f32_16x16x32_bf16 v[60:63], v[142:145], v[200:203], v[60:63]
	v_mfma_f32_16x16x32_bf16 v[20:23], v[150:153], v[200:203], v[20:23]
	v_mfma_f32_16x16x32_bf16 v[108:111], v[142:145], v[218:221], v[108:111]
	v_mfma_f32_16x16x32_bf16 v[104:107], v[150:153], v[218:221], v[104:107]
	v_mfma_f32_16x16x32_bf16 v[124:127], v[146:149], v[182:185], v[124:127]
	v_mfma_f32_16x16x32_bf16 v[120:123], v[154:157], v[182:185], v[120:123]
	v_mfma_f32_16x16x32_bf16 v[68:71], v[146:149], v[196:199], v[68:71]
	v_mfma_f32_16x16x32_bf16 v[64:67], v[154:157], v[196:199], v[64:67]
	v_mfma_f32_16x16x32_bf16 v[60:63], v[146:149], v[204:207], v[60:63]
	v_mfma_f32_16x16x32_bf16 v[20:23], v[154:157], v[204:207], v[20:23]
	v_mfma_f32_16x16x32_bf16 v[108:111], v[146:149], v[222:225], v[108:111]
	v_mfma_f32_16x16x32_bf16 v[104:107], v[154:157], v[222:225], v[104:107]
	s_setprio 0
	s_setprio 1
	v_mfma_f32_16x16x32_bf16 v[116:119], v[158:161], v[178:181], v[116:119]
	v_mfma_f32_16x16x32_bf16 v[112:115], v[166:169], v[178:181], v[112:115]
	v_mfma_f32_16x16x32_bf16 v[52:55], v[158:161], v[186:189], v[52:55]
	v_mfma_f32_16x16x32_bf16 v[48:51], v[166:169], v[186:189], v[48:51]
	v_mfma_f32_16x16x32_bf16 v[44:47], v[158:161], v[200:203], v[44:47]
	v_mfma_f32_16x16x32_bf16 v[16:19], v[166:169], v[200:203], v[16:19]
	v_mfma_f32_16x16x32_bf16 v[100:103], v[158:161], v[218:221], v[100:103]
	v_mfma_f32_16x16x32_bf16 v[96:99], v[166:169], v[218:221], v[96:99]
	v_mfma_f32_16x16x32_bf16 v[116:119], v[162:165], v[182:185], v[116:119]
	v_mfma_f32_16x16x32_bf16 v[112:115], v[170:173], v[182:185], v[112:115]
	v_mfma_f32_16x16x32_bf16 v[52:55], v[162:165], v[196:199], v[52:55]
	v_mfma_f32_16x16x32_bf16 v[48:51], v[170:173], v[196:199], v[48:51]
	v_mfma_f32_16x16x32_bf16 v[44:47], v[162:165], v[204:207], v[44:47]
	v_mfma_f32_16x16x32_bf16 v[16:19], v[170:173], v[204:207], v[16:19]
	v_mfma_f32_16x16x32_bf16 v[100:103], v[162:165], v[222:225], v[100:103]
	s_setprio 2
	s_barrier
; #define PG8_STAGE(bufoff, gbase, voff) do { _Pragma("unroll") for (int _i = 0; _i < 2; ++_i) \
;         __builtin_amdgcn_global_load_lds((const unsigned*)((const char*)(gbase) + (voff)[_i]), (LAS unsigned*)(lds + (bufoff) + ldsw + _i * 8192), 16, 0, 0); } while (0)
; #define PG8_LDA(dst, b, h) do { _Pragma("unroll") for (int m = 0; m < 4; ++m) _Pragma("unroll") for (int k = 0; k < 2; ++k) dst[m][k] = *(const LAS bf16x8*)(lds + PG8_SA(b, h) + aoff + m * 2048 + k * 1024); } while (0)
; #define PG8_MMA(ai, bj, At, Bt) do { __builtin_amdgcn_s_setprio(1); _Pragma("unroll") for (int m = 0; m < 4; ++m) _Pragma("unroll") for (int n = 0; n < 2; ++n) _Pragma("unroll") for (int k = 0; k < 2; ++k) \
;         acc[ai][bj][m][n] = __builtin_amdgcn_mfma_f32_16x16x32_bf16(Bt[n][k], At[m][k], acc[ai][bj][m][n], 0, 0, 0); __builtin_amdgcn_s_setprio(0); } while (0)
; #define PG8_WAIT_V(n) asm volatile("s_waitcnt vmcnt(" #n ")" ::: "memory")
; #define PG8_WAIT_L(n) asm volatile("s_waitcnt lgkmcnt(" #n ")" ::: "memory")
; #define PG8_BAR __builtin_amdgcn_s_barrier()
; #define PG8_SCHED __builtin_amdgcn_sched_barrier(0)
; template <class Epi, bool KREV = false>
; __device__ __forceinline__ void gemm_phase(LAS unsigned char* lds, const Gemm g, const StaticOrder& S, const Epi& E, int wave_s) {
;     ...
;             PG8_LDA(At, 1, 1); PG8_STAGE(PG8_SB(1, 0), b3, voffB); PG8_STAGE(PG8_SB(1, 1), b3 + bh, voffB); PG8_STAGE(PG8_SA(1, 0), a3, voffA);
;             PG8_WAIT_V(8); PG8_WAIT_L(0); PG8_BAR; PG8_MMA(1, 0, At, B0); PG8_MMA(1, 1, At, B1); PG8_BAR; PG8_SCHED;
;         }
;         if (wr == 0) PG8_BAR;
	v_mfma_f32_16x16x32_bf16 v[96:99], v[170:173], v[222:225], v[96:99]
	s_setprio 0
	s_add_i32 s58, s84, s66
	s_mov_b32 m0, s58
	ds_read_b128 v[178:181], v194 offset:49152
	ds_read_b128 v[182:185], v194 offset:50176
	ds_read_b128 v[186:189], v194 offset:51200
	ds_read_b128 v[196:199], v194 offset:52224
	ds_read_b128 v[200:203], v194 offset:53248
	ds_read_b128 v[204:207], v194 offset:54272
	ds_read_b128 v[218:221], v194 offset:55296
	ds_read_b128 v[222:225], v194 offset:56320
	global_load_lds_dwordx4 v176, s[98:99]
	s_add_i32 m0, s58, 0x2000
	s_add_u32 s56, s56, 0x1600080
	s_addc_u32 s57, s57, 0
	s_add_i32 s58, s85, s66
	global_load_lds_dwordx4 v132, s[98:99]
	s_mov_b32 m0, s58
	s_nop 0
	global_load_lds_dwordx4 v176, s[56:57]
	s_add_i32 m0, s58, 0x2000
	s_nop 0
	global_load_lds_dwordx4 v132, s[56:57]
	s_mov_b32 m0, s70
	s_nop 0
	global_load_lds_dwordx4 v128, s[100:101]
	s_mov_b32 m0, s71
	s_nop 0
	global_load_lds_dwordx4 v130, s[100:101]
	s_waitcnt vmcnt(8)
	s_waitcnt lgkmcnt(0)
	s_barrier
	s_setprio 1
	s_waitcnt lgkmcnt(0)
	v_mfma_f32_16x16x32_bf16 v[92:95], v[142:145], v[178:181], v[92:95]
	v_mfma_f32_16x16x32_bf16 v[88:91], v[150:153], v[178:181], v[88:91]
	v_mfma_f32_16x16x32_bf16 v[36:39], v[142:145], v[186:189], v[36:39]
	v_mfma_f32_16x16x32_bf16 v[12:15], v[150:153], v[186:189], v[12:15]
	v_mfma_f32_16x16x32_bf16 v[32:35], v[142:145], v[200:203], v[32:35]
	v_mfma_f32_16x16x32_bf16 v[4:7], v[150:153], v[200:203], v[4:7]
	v_mfma_f32_16x16x32_bf16 v[76:79], v[142:145], v[218:221], v[76:79]
	v_mfma_f32_16x16x32_bf16 v[56:59], v[150:153], v[218:221], v[56:59]
	v_mfma_f32_16x16x32_bf16 v[92:95], v[146:149], v[182:185], v[92:95]
	v_mfma_f32_16x16x32_bf16 v[88:91], v[154:157], v[182:185], v[88:91]
	v_mfma_f32_16x16x32_bf16 v[36:39], v[146:149], v[196:199], v[36:39]
	v_mfma_f32_16x16x32_bf16 v[12:15], v[154:157], v[196:199], v[12:15]
	v_mfma_f32_16x16x32_bf16 v[32:35], v[146:149], v[204:207], v[32:35]
	v_mfma_f32_16x16x32_bf16 v[4:7], v[154:157], v[204:207], v[4:7]
	v_mfma_f32_16x16x32_bf16 v[76:79], v[146:149], v[222:225], v[76:79]
	v_mfma_f32_16x16x32_bf16 v[56:59], v[154:157], v[222:225], v[56:59]
	s_setprio 0
	s_setprio 1
	v_mfma_f32_16x16x32_bf16 v[84:87], v[158:161], v[178:181], v[84:87]
	v_mfma_f32_16x16x32_bf16 v[80:83], v[166:169], v[178:181], v[80:83]
	v_mfma_f32_16x16x32_bf16 v[28:31], v[158:161], v[186:189], v[28:31]
	v_mfma_f32_16x16x32_bf16 v[8:11], v[166:169], v[186:189], v[8:11]
	v_mfma_f32_16x16x32_bf16 v[24:27], v[158:161], v[200:203], v[24:27]
	v_mfma_f32_16x16x32_bf16 v[0:3], v[166:169], v[200:203], v[0:3]
	v_mfma_f32_16x16x32_bf16 v[72:75], v[158:161], v[218:221], v[72:75]
	v_mfma_f32_16x16x32_bf16 v[40:43], v[166:169], v[218:221], v[40:43]
	v_mfma_f32_16x16x32_bf16 v[84:87], v[162:165], v[182:185], v[84:87]
	v_mfma_f32_16x16x32_bf16 v[80:83], v[170:173], v[182:185], v[80:83]
	v_mfma_f32_16x16x32_bf16 v[28:31], v[162:165], v[196:199], v[28:31]
	v_mfma_f32_16x16x32_bf16 v[8:11], v[170:173], v[196:199], v[8:11]
	s_add_i32 s83, s83, 2
	s_add_u32 s54, s54, 0x100
	s_addc_u32 s55, s55, 0
	v_mfma_f32_16x16x32_bf16 v[24:27], v[162:165], v[204:207], v[24:27]
	s_add_u32 s80, s80, 0x100
	s_addc_u32 s82, s82, 0
	v_mfma_f32_16x16x32_bf16 v[0:3], v[170:173], v[204:207], v[0:3]
	s_cmp_gt_u32 s83, 29
	v_mfma_f32_16x16x32_bf16 v[72:75], v[162:165], v[222:225], v[72:75]
	s_setprio 2
	s_barrier
	v_mfma_f32_16x16x32_bf16 v[40:43], v[170:173], v[222:225], v[40:43]
	s_setprio 0
	s_cbranch_scc0 .LBB0_836
	s_and_b64 vcc, exec, s[38:39]
	s_cbranch_vccz .LBB0_839
	s_barrier

; #define PG8_STAGE(bufoff, gbase, voff) do { _Pragma("unroll") for (int _i = 0; _i < 2; ++_i) \
;         __builtin_amdgcn_global_load_lds((const unsigned*)((const char*)(gbase) + (voff)[_i]), (LAS unsigned*)(lds + (bufoff) + ldsw + _i * 8192), 16, 0, 0); } while (0)
; #define PG8_LDA(dst, b, h) do { _Pragma("unroll") for (int m = 0; m < 4; ++m) _Pragma("unroll") for (int k = 0; k < 2; ++k) dst[m][k] = *(const LAS bf16x8*)(lds + PG8_SA(b, h) + aoff + m * 2048 + k * 1024); } while (0)
; #define PG8_LDB(dst, b, h) do { _Pragma("unroll") for (int n = 0; n < 2; ++n) _Pragma("unroll") for (int k = 0; k < 2; ++k) dst[n][k] = *(const LAS bf16x8*)(lds + PG8_SB(b, h) + boff + n * 2048 + k * 1024); } while (0)
; #define PG8_MMA(ai, bj, At, Bt) do { __builtin_amdgcn_s_setprio(1); _Pragma("unroll") for (int m = 0; m < 4; ++m) _Pragma("unroll") for (int n = 0; n < 2; ++n) _Pragma("unroll") for (int k = 0; k < 2; ++k) \
;         acc[ai][bj][m][n] = __builtin_amdgcn_mfma_f32_16x16x32_bf16(Bt[n][k], At[m][k], acc[ai][bj][m][n], 0, 0, 0); __builtin_amdgcn_s_setprio(0); } while (0)
; #define PG8_WAIT_V(n) asm volatile("s_waitcnt vmcnt(" #n ")" ::: "memory")
; #define PG8_WAIT_L(n) asm volatile("s_waitcnt lgkmcnt(" #n ")" ::: "memory")
; #define PG8_BAR __builtin_amdgcn_s_barrier()
; #define PG8_SCHED __builtin_amdgcn_sched_barrier(0)
; template <class Epi, bool KREV = false>
; __device__ __forceinline__ void gemm_phase(LAS unsigned char* lds, const Gemm g, const StaticOrder& S, const Epi& E, int wave_s) {
;     ...
;             const char* a1 = cA + (size_t)(t + 1) * kstep;
;             const char* a2 = last ? nA : cA + (size_t)(t + 2) * kstep; const char* b2 = last ? nB : cB + (size_t)(t + 2) * kstep;
;             const char* a3 = a2 + kstep; const char* b3 = b2 + kstep;
;             PG8_LDB(B0, 0, 0); PG8_LDB(B1, 0, 1); PG8_SCHED; PG8_LDA(At, 0, 0); PG8_STAGE(PG8_SA(1, 1), a1 + hstep, voffA);
;             PG8_WAIT_V(8); PG8_WAIT_L(0); PG8_BAR; PG8_MMA(0, 0, At, B0); PG8_MMA(0, 1, At, B1); PG8_BAR; PG8_SCHED;
;             PG8_LDA(At, 0, 1); PG8_STAGE(PG8_SB(0, 0), b2, voffB); PG8_STAGE(PG8_SB(0, 1), b2 + bh, voffB); PG8_STAGE(PG8_SA(0, 0), a2, voffA);
;             PG8_WAIT_V(8); PG8_WAIT_L(0); PG8_BAR; PG8_MMA(1, 0, At, B0); PG8_MMA(1, 1, At, B1); PG8_BAR; PG8_SCHED;
.LBB0_1023:
	s_or_b32 s80, s44, 1
	s_lshl_b64 s[46:47], s[80:81], 7
	s_sub_u32 s23, 0, s46
	s_subb_u32 s45, 0, s47
	s_add_i32 s48, 0, 0x10000
	s_add_i32 s49, 0, 0x14000
	s_add_u32 s46, s42, s23
	s_addc_u32 s47, s43, s45
	s_add_i32 m0, s28, 0xc000
	s_nop 0
	global_load_lds_dwordx4 v156, s[46:47]
	s_add_i32 m0, s28, 0xe000
	s_nop 0
	global_load_lds_dwordx4 v154, s[46:47]
	s_waitcnt vmcnt(8)
	s_waitcnt lgkmcnt(0)
	s_barrier
	s_setprio 1
	s_waitcnt lgkmcnt(0)
	v_mfma_f32_16x16x32_bf16 v[132:135], v[112:115], v[218:221], v[132:135]
	v_mfma_f32_16x16x32_bf16 v[120:123], v[136:139], v[218:221], v[120:123]
	v_mfma_f32_16x16x32_bf16 v[108:111], v[112:115], v[226:229], v[108:111]
	v_mfma_f32_16x16x32_bf16 v[104:107], v[136:139], v[226:229], v[104:107]
	v_mfma_f32_16x16x32_bf16 v[92:95], v[112:115], v[234:237], v[92:95]
	v_mfma_f32_16x16x32_bf16 v[88:91], v[136:139], v[234:237], v[88:91]
	v_mfma_f32_16x16x32_bf16 v[76:79], v[112:115], v[242:245], v[76:79]
	v_mfma_f32_16x16x32_bf16 v[72:75], v[136:139], v[242:245], v[72:75]
	v_mfma_f32_16x16x32_bf16 v[132:135], v[124:127], v[222:225], v[132:135]
	v_mfma_f32_16x16x32_bf16 v[120:123], v[140:143], v[222:225], v[120:123]
	v_mfma_f32_16x16x32_bf16 v[108:111], v[124:127], v[230:233], v[108:111]
	v_mfma_f32_16x16x32_bf16 v[104:107], v[140:143], v[230:233], v[104:107]
	v_mfma_f32_16x16x32_bf16 v[92:95], v[124:127], v[238:241], v[92:95]
	v_mfma_f32_16x16x32_bf16 v[88:91], v[140:143], v[238:241], v[88:91]
	v_mfma_f32_16x16x32_bf16 v[76:79], v[124:127], v[246:249], v[76:79]
	v_mfma_f32_16x16x32_bf16 v[72:75], v[140:143], v[246:249], v[72:75]
	s_setprio 0
	s_setprio 1
	v_mfma_f32_16x16x32_bf16 v[128:131], v[144:147], v[218:221], v[128:131]
	v_mfma_f32_16x16x32_bf16 v[116:119], v[194:197], v[218:221], v[116:119]
	v_mfma_f32_16x16x32_bf16 v[100:103], v[144:147], v[226:229], v[100:103]
	v_mfma_f32_16x16x32_bf16 v[96:99], v[194:197], v[226:229], v[96:99]
	v_mfma_f32_16x16x32_bf16 v[84:87], v[144:147], v[234:237], v[84:87]
	v_mfma_f32_16x16x32_bf16 v[80:83], v[194:197], v[234:237], v[80:83]
	v_mfma_f32_16x16x32_bf16 v[68:71], v[144:147], v[242:245], v[68:71]
	v_mfma_f32_16x16x32_bf16 v[64:67], v[194:197], v[242:245], v[64:67]
	v_mfma_f32_16x16x32_bf16 v[128:131], v[148:151], v[222:225], v[128:131]
	v_mfma_f32_16x16x32_bf16 v[116:119], v[202:205], v[222:225], v[116:119]
	v_mfma_f32_16x16x32_bf16 v[100:103], v[148:151], v[230:233], v[100:103]
	v_mfma_f32_16x16x32_bf16 v[96:99], v[202:205], v[230:233], v[96:99]
	v_mfma_f32_16x16x32_bf16 v[84:87], v[148:151], v[238:241], v[84:87]
	v_mfma_f32_16x16x32_bf16 v[80:83], v[202:205], v[238:241], v[80:83]
	v_mfma_f32_16x16x32_bf16 v[68:71], v[148:151], v[246:249], v[68:71]
	s_setprio 2
	s_barrier
	v_mfma_f32_16x16x32_bf16 v[64:67], v[202:205], v[246:249], v[64:67]
	s_setprio 0
	s_add_u32 s98, s24, s78
	s_addc_u32 s99, s25, s79
	s_add_u32 s100, s26, s78
	s_addc_u32 s101, s27, s79
	s_add_i32 s23, s48, s1
	s_mov_b32 m0, s23
	ds_read_b128 v[218:221], v201 offset:16384
	ds_read_b128 v[222:225], v201 offset:17408
	ds_read_b128 v[226:229], v201 offset:18432
	ds_read_b128 v[230:233], v201 offset:19456
	ds_read_b128 v[234:237], v201 offset:20480
	ds_read_b128 v[238:241], v201 offset:21504
	ds_read_b128 v[242:245], v201 offset:22528
	ds_read_b128 v[246:249], v201 offset:23552
	global_load_lds_dwordx4 v176, s[24:25]
	s_add_i32 m0, s23, 0x2000
	s_add_u32 s46, s24, 0x160000
	s_addc_u32 s47, s25, 0
	s_add_i32 s23, s49, s1
	global_load_lds_dwordx4 v152, s[24:25]
	s_mov_b32 m0, s23
	s_nop 0
	global_load_lds_dwordx4 v176, s[46:47]
	s_add_i32 m0, s23, 0x2000
	s_nop 0
	global_load_lds_dwordx4 v152, s[46:47]
	s_mov_b32 m0, s28
	s_nop 0
	global_load_lds_dwordx4 v156, s[26:27]
	s_mov_b32 m0, s29
	s_nop 0
	global_load_lds_dwordx4 v154, s[26:27]
	s_waitcnt vmcnt(8)
	s_waitcnt lgkmcnt(0)
	s_barrier
	s_setprio 1
	s_waitcnt lgkmcnt(0)
	v_mfma_f32_16x16x32_bf16 v[60:63], v[112:115], v[218:221], v[60:63]
	v_mfma_f32_16x16x32_bf16 v[56:59], v[136:139], v[218:221], v[56:59]
	v_mfma_f32_16x16x32_bf16 v[44:47], v[112:115], v[226:229], v[44:47]
	v_mfma_f32_16x16x32_bf16 v[40:43], v[136:139], v[226:229], v[40:43]
	v_mfma_f32_16x16x32_bf16 v[28:31], v[112:115], v[234:237], v[28:31]
	v_mfma_f32_16x16x32_bf16 v[24:27], v[136:139], v[234:237], v[24:27]
	v_mfma_f32_16x16x32_bf16 v[12:15], v[112:115], v[242:245], v[12:15]
	v_mfma_f32_16x16x32_bf16 v[8:11], v[136:139], v[242:245], v[8:11]
	v_mfma_f32_16x16x32_bf16 v[60:63], v[124:127], v[222:225], v[60:63]
	v_mfma_f32_16x16x32_bf16 v[56:59], v[140:143], v[222:225], v[56:59]
	v_mfma_f32_16x16x32_bf16 v[44:47], v[124:127], v[230:233], v[44:47]
	v_mfma_f32_16x16x32_bf16 v[40:43], v[140:143], v[230:233], v[40:43]
	v_mfma_f32_16x16x32_bf16 v[28:31], v[124:127], v[238:241], v[28:31]
	v_mfma_f32_16x16x32_bf16 v[24:27], v[140:143], v[238:241], v[24:27]
	v_mfma_f32_16x16x32_bf16 v[12:15], v[124:127], v[246:249], v[12:15]
	v_mfma_f32_16x16x32_bf16 v[8:11], v[140:143], v[246:249], v[8:11]
	s_setprio 0
	s_setprio 1
	v_mfma_f32_16x16x32_bf16 v[52:55], v[144:147], v[218:221], v[52:55]
	v_mfma_f32_16x16x32_bf16 v[48:51], v[194:197], v[218:221], v[48:51]
	v_mfma_f32_16x16x32_bf16 v[36:39], v[144:147], v[226:229], v[36:39]
	v_mfma_f32_16x16x32_bf16 v[32:35], v[194:197], v[226:229], v[32:35]
	v_mfma_f32_16x16x32_bf16 v[20:23], v[144:147], v[234:237], v[20:23]
	v_mfma_f32_16x16x32_bf16 v[16:19], v[194:197], v[234:237], v[16:19]
	v_mfma_f32_16x16x32_bf16 v[4:7], v[144:147], v[242:245], v[4:7]
	v_mfma_f32_16x16x32_bf16 v[0:3], v[194:197], v[242:245], v[0:3]
	v_mfma_f32_16x16x32_bf16 v[52:55], v[148:151], v[222:225], v[52:55]
	v_mfma_f32_16x16x32_bf16 v[48:51], v[202:205], v[222:225], v[48:51]
	v_mfma_f32_16x16x32_bf16 v[36:39], v[148:151], v[230:233], v[36:39]
	v_mfma_f32_16x16x32_bf16 v[32:35], v[202:205], v[230:233], v[32:35]
	v_mfma_f32_16x16x32_bf16 v[20:23], v[148:151], v[238:241], v[20:23]
	v_mfma_f32_16x16x32_bf16 v[16:19], v[202:205], v[238:241], v[16:19]
	v_mfma_f32_16x16x32_bf16 v[4:7], v[148:151], v[246:249], v[4:7]
	s_setprio 2
	s_barrier
; #define PG8_STAGE(bufoff, gbase, voff) do { _Pragma("unroll") for (int _i = 0; _i < 2; ++_i) \
;         __builtin_amdgcn_global_load_lds((const unsigned*)((const char*)(gbase) + (voff)[_i]), (LAS unsigned*)(lds + (bufoff) + ldsw + _i * 8192), 16, 0, 0); } while (0)
; #define PG8_LDA(dst, b, h) do { _Pragma("unroll") for (int m = 0; m < 4; ++m) _Pragma("unroll") for (int k = 0; k < 2; ++k) dst[m][k] = *(const LAS bf16x8*)(lds + PG8_SA(b, h) + aoff + m * 2048 + k * 1024); } while (0)
; #define PG8_LDB(dst, b, h) do { _Pragma("unroll") for (int n = 0; n < 2; ++n) _Pragma("unroll") for (int k = 0; k < 2; ++k) dst[n][k] = *(const LAS bf16x8*)(lds + PG8_SB(b, h) + boff + n * 2048 + k * 1024); } while (0)
; #define PG8_MMA(ai, bj, At, Bt) do { __builtin_amdgcn_s_setprio(1); _Pragma("unroll") for (int m = 0; m < 4; ++m) _Pragma("unroll") for (int n = 0; n < 2; ++n) _Pragma("unroll") for (int k = 0; k < 2; ++k) \
;         acc[ai][bj][m][n] = __builtin_amdgcn_mfma_f32_16x16x32_bf16(Bt[n][k], At[m][k], acc[ai][bj][m][n], 0, 0, 0); __builtin_amdgcn_s_setprio(0); } while (0)
; #define PG8_WAIT_V(n) asm volatile("s_waitcnt vmcnt(" #n ")" ::: "memory")
; #define PG8_WAIT_L(n) asm volatile("s_waitcnt lgkmcnt(" #n ")" ::: "memory")
; #define PG8_BAR __builtin_amdgcn_s_barrier()
; #define PG8_SCHED __builtin_amdgcn_sched_barrier(0)
; template <class Epi, bool KREV = false>
; __device__ __forceinline__ void gemm_phase(LAS unsigned char* lds, const Gemm g, const StaticOrder& S, const Epi& E, int wave_s) {
;     ...
;             PG8_LDB(B0, 1, 0); PG8_LDB(B1, 1, 1); PG8_SCHED; PG8_LDA(At, 1, 0); PG8_STAGE(PG8_SA(0, 1), a2 + hstep, voffA);
;             PG8_WAIT_V(8); PG8_WAIT_L(0); PG8_BAR; PG8_MMA(0, 0, At, B0); PG8_MMA(0, 1, At, B1); PG8_BAR; PG8_SCHED;
;             PG8_LDA(At, 1, 1); PG8_STAGE(PG8_SB(1, 0), b3, voffB); PG8_STAGE(PG8_SB(1, 1), b3 + bh, voffB); PG8_STAGE(PG8_SA(1, 0), a3, voffA);
;             PG8_WAIT_V(8); PG8_WAIT_L(0); PG8_BAR; PG8_MMA(1, 0, At, B0); PG8_MMA(1, 1, At, B1); PG8_BAR; PG8_SCHED;
;         }
	v_mfma_f32_16x16x32_bf16 v[0:3], v[202:205], v[246:249], v[0:3]
	s_setprio 0
	s_add_i32 s23, 0, 0x18000
	s_add_i32 s45, 0, 0x1c000
	v_add_u32_e32 v140, s23, v199
	v_add_u32_e32 v202, s45, v199
	ds_read_b128 v[112:115], v140
	ds_read_b128 v[124:127], v140 offset:1024
	ds_read_b128 v[136:139], v140 offset:2048
	ds_read_b128 v[140:143], v140 offset:3072
	ds_read_b128 v[144:147], v202
	ds_read_b128 v[148:151], v202 offset:1024
	ds_read_b128 v[194:197], v202 offset:2048
	ds_read_b128 v[202:205], v202 offset:3072
	s_add_u32 s26, s26, 0x160000
	s_addc_u32 s27, s27, 0
	s_mov_b32 m0, s30
	ds_read_b128 v[218:221], v201 offset:32768
	ds_read_b128 v[222:225], v201 offset:33792
	ds_read_b128 v[226:229], v201 offset:34816
	ds_read_b128 v[230:233], v201 offset:35840
	ds_read_b128 v[234:237], v201 offset:36864
	ds_read_b128 v[238:241], v201 offset:37888
	ds_read_b128 v[242:245], v201 offset:38912
	ds_read_b128 v[246:249], v201 offset:39936
	global_load_lds_dwordx4 v156, s[26:27]
	s_mov_b32 m0, s34
	s_nop 0
	global_load_lds_dwordx4 v154, s[26:27]
	s_waitcnt vmcnt(8)
	s_waitcnt lgkmcnt(0)
	s_barrier
	s_setprio 1
	s_waitcnt lgkmcnt(0)
	v_mfma_f32_16x16x32_bf16 v[132:135], v[112:115], v[218:221], v[132:135]
	v_mfma_f32_16x16x32_bf16 v[120:123], v[136:139], v[218:221], v[120:123]
	v_mfma_f32_16x16x32_bf16 v[108:111], v[112:115], v[226:229], v[108:111]
	v_mfma_f32_16x16x32_bf16 v[104:107], v[136:139], v[226:229], v[104:107]
	v_mfma_f32_16x16x32_bf16 v[92:95], v[112:115], v[234:237], v[92:95]
	v_mfma_f32_16x16x32_bf16 v[88:91], v[136:139], v[234:237], v[88:91]
	v_mfma_f32_16x16x32_bf16 v[76:79], v[112:115], v[242:245], v[76:79]
	v_mfma_f32_16x16x32_bf16 v[72:75], v[136:139], v[242:245], v[72:75]
	v_mfma_f32_16x16x32_bf16 v[132:135], v[124:127], v[222:225], v[132:135]
	v_mfma_f32_16x16x32_bf16 v[120:123], v[140:143], v[222:225], v[120:123]
	v_mfma_f32_16x16x32_bf16 v[108:111], v[124:127], v[230:233], v[108:111]
	v_mfma_f32_16x16x32_bf16 v[104:107], v[140:143], v[230:233], v[104:107]
	v_mfma_f32_16x16x32_bf16 v[92:95], v[124:127], v[238:241], v[92:95]
	v_mfma_f32_16x16x32_bf16 v[88:91], v[140:143], v[238:241], v[88:91]
	v_mfma_f32_16x16x32_bf16 v[76:79], v[124:127], v[246:249], v[76:79]
	v_mfma_f32_16x16x32_bf16 v[72:75], v[140:143], v[246:249], v[72:75]
	s_setprio 0
	s_setprio 1
	v_mfma_f32_16x16x32_bf16 v[128:131], v[144:147], v[218:221], v[128:131]
	v_mfma_f32_16x16x32_bf16 v[116:119], v[194:197], v[218:221], v[116:119]
	v_mfma_f32_16x16x32_bf16 v[100:103], v[144:147], v[226:229], v[100:103]
	v_mfma_f32_16x16x32_bf16 v[96:99], v[194:197], v[226:229], v[96:99]
	v_mfma_f32_16x16x32_bf16 v[84:87], v[144:147], v[234:237], v[84:87]
	v_mfma_f32_16x16x32_bf16 v[80:83], v[194:197], v[234:237], v[80:83]
	v_mfma_f32_16x16x32_bf16 v[68:71], v[144:147], v[242:245], v[68:71]
	v_mfma_f32_16x16x32_bf16 v[64:67], v[194:197], v[242:245], v[64:67]
	v_mfma_f32_16x16x32_bf16 v[128:131], v[148:151], v[222:225], v[128:131]
	v_mfma_f32_16x16x32_bf16 v[116:119], v[202:205], v[222:225], v[116:119]
	v_mfma_f32_16x16x32_bf16 v[100:103], v[148:151], v[230:233], v[100:103]
	v_mfma_f32_16x16x32_bf16 v[96:99], v[202:205], v[230:233], v[96:99]
	v_mfma_f32_16x16x32_bf16 v[84:87], v[148:151], v[238:241], v[84:87]
	v_mfma_f32_16x16x32_bf16 v[80:83], v[202:205], v[238:241], v[80:83]
	v_mfma_f32_16x16x32_bf16 v[68:71], v[148:151], v[246:249], v[68:71]
	s_setprio 2
	s_barrier
	v_mfma_f32_16x16x32_bf16 v[64:67], v[202:205], v[246:249], v[64:67]
	s_setprio 0
	s_add_i32 s23, s23, s1
	s_mov_b32 m0, s23
	ds_read_b128 v[218:221], v201 offset:49152
	ds_read_b128 v[222:225], v201 offset:50176
	ds_read_b128 v[226:229], v201 offset:51200
	ds_read_b128 v[230:233], v201 offset:52224
	ds_read_b128 v[234:237], v201 offset:53248
	ds_read_b128 v[238:241], v201 offset:54272
	ds_read_b128 v[242:245], v201 offset:55296
	ds_read_b128 v[246:249], v201 offset:56320
	global_load_lds_dwordx4 v176, s[98:99]
	s_add_i32 m0, s23, 0x2000
	s_add_u32 s24, s24, 0x15ff80
	s_addc_u32 s25, s25, 0
	s_add_i32 s23, s45, s1
	global_load_lds_dwordx4 v152, s[98:99]
	s_mov_b32 m0, s23
	s_nop 0
	global_load_lds_dwordx4 v176, s[24:25]
	s_add_i32 m0, s23, 0x2000
	s_nop 0
	global_load_lds_dwordx4 v152, s[24:25]
	s_mov_b32 m0, s36
	s_nop 0
	global_load_lds_dwordx4 v156, s[100:101]
	s_mov_b32 m0, s37
	s_nop 0
	global_load_lds_dwordx4 v154, s[100:101]
	s_waitcnt vmcnt(8)
	s_waitcnt lgkmcnt(0)
	s_barrier
	s_setprio 1
	s_waitcnt lgkmcnt(0)
	v_mfma_f32_16x16x32_bf16 v[60:63], v[112:115], v[218:221], v[60:63]
	v_mfma_f32_16x16x32_bf16 v[56:59], v[136:139], v[218:221], v[56:59]
	v_mfma_f32_16x16x32_bf16 v[44:47], v[112:115], v[226:229], v[44:47]
	v_mfma_f32_16x16x32_bf16 v[40:43], v[136:139], v[226:229], v[40:43]
	v_mfma_f32_16x16x32_bf16 v[28:31], v[112:115], v[234:237], v[28:31]
	v_mfma_f32_16x16x32_bf16 v[24:27], v[136:139], v[234:237], v[24:27]
	v_mfma_f32_16x16x32_bf16 v[12:15], v[112:115], v[242:245], v[12:15]
	v_mfma_f32_16x16x32_bf16 v[8:11], v[136:139], v[242:245], v[8:11]
	v_mfma_f32_16x16x32_bf16 v[60:63], v[124:127], v[222:225], v[60:63]
	v_mfma_f32_16x16x32_bf16 v[56:59], v[140:143], v[222:225], v[56:59]
	v_mfma_f32_16x16x32_bf16 v[44:47], v[124:127], v[230:233], v[44:47]
	v_mfma_f32_16x16x32_bf16 v[40:43], v[140:143], v[230:233], v[40:43]
	v_mfma_f32_16x16x32_bf16 v[28:31], v[124:127], v[238:241], v[28:31]
	v_mfma_f32_16x16x32_bf16 v[24:27], v[140:143], v[238:241], v[24:27]
	v_mfma_f32_16x16x32_bf16 v[12:15], v[124:127], v[246:249], v[12:15]
	v_mfma_f32_16x16x32_bf16 v[8:11], v[140:143], v[246:249], v[8:11]
	s_setprio 0
	s_setprio 1
	v_mfma_f32_16x16x32_bf16 v[52:55], v[144:147], v[218:221], v[52:55]
	v_mfma_f32_16x16x32_bf16 v[48:51], v[194:197], v[218:221], v[48:51]
	v_mfma_f32_16x16x32_bf16 v[36:39], v[144:147], v[226:229], v[36:39]
	v_mfma_f32_16x16x32_bf16 v[32:35], v[194:197], v[226:229], v[32:35]
	v_mfma_f32_16x16x32_bf16 v[20:23], v[144:147], v[234:237], v[20:23]
	v_mfma_f32_16x16x32_bf16 v[16:19], v[194:197], v[234:237], v[16:19]
	v_mfma_f32_16x16x32_bf16 v[4:7], v[144:147], v[242:245], v[4:7]
	v_mfma_f32_16x16x32_bf16 v[0:3], v[194:197], v[242:245], v[0:3]
	v_mfma_f32_16x16x32_bf16 v[52:55], v[148:151], v[222:225], v[52:55]
	v_mfma_f32_16x16x32_bf16 v[48:51], v[202:205], v[222:225], v[48:51]
	v_mfma_f32_16x16x32_bf16 v[36:39], v[148:151], v[230:233], v[36:39]
	v_mfma_f32_16x16x32_bf16 v[32:35], v[202:205], v[230:233], v[32:35]
	s_cmpk_gt_u32 s44, 0x55
	s_mov_b32 s44, s22
	v_mfma_f32_16x16x32_bf16 v[20:23], v[148:151], v[238:241], v[20:23]
	v_mfma_f32_16x16x32_bf16 v[16:19], v[202:205], v[238:241], v[16:19]
	v_mfma_f32_16x16x32_bf16 v[4:7], v[148:151], v[246:249], v[4:7]
	s_setprio 2
	s_barrier
	v_mfma_f32_16x16x32_bf16 v[0:3], v[202:205], v[246:249], v[0:3]
	s_setprio 0
	s_cbranch_scc1 .LBB0_1028
